# stack1 + nt on the remaining wide stores (P0 U / weight images, deferred conversions, attention and retention outputs)
# baseline (speedup 1.0000x reference)
.LBB0_38:
	v_mul_hi_i32 v11, v6, s5
	v_lshrrev_b32_e32 v14, 31, v11
	v_ashrrev_i32_e32 v11, 13, v11
	v_add_u32_e32 v11, v11, v14
	v_mul_i32_i24_e32 v11, 0xc000, v11
	v_sub_u32_e32 v11, v6, v11
	v_mul_hi_i32 v14, v11, s5
	v_lshrrev_b32_e32 v15, 31, v14
	v_ashrrev_i32_e32 v14, 7, v14
	v_add_u32_e32 v14, v14, v15
	v_add_u32_e32 v12, 0xbfff, v6
	v_mul_i32_i24_e32 v15, 0x300, v14
	v_mul_i32_i24_e32 v14, 0x1040, v14
	v_cmp_gt_u32_e32 vcc, s6, v12
	v_sub_u32_e32 v16, v11, v15
	v_ashrrev_i32_e32 v15, 31, v14
	v_cndmask_b32_e32 v13, v7, v8, vcc
	v_cndmask_b32_e32 v12, v9, v10, vcc
	v_add_u32_e32 v6, s4, v6
	v_lshlrev_b64 v[14:15], 8, v[14:15]
	v_cmp_lt_i32_e32 vcc, s6, v6
	v_ashrrev_i32_e32 v17, 31, v16
	v_lshl_add_u64 v[12:13], v[12:13], 0, v[14:15]
	s_or_b64 s[2:3], vcc, s[2:3]
	v_lshl_add_u64 v[12:13], v[16:17], 4, v[12:13]
	global_store_dwordx4 v[12:13], v[2:5], off nt
	s_andn2_b64 exec, exec, s[2:3]
	s_cbranch_execnz .LBB0_38

.LBB0_41:
	s_mul_hi_i32 s0, s6, 0x92492493
	s_add_i32 s0, s0, s6
	s_lshr_b32 s1, s0, 31
	s_lshr_b32 s0, s0, 7
	s_add_i32 s0, s0, s1
	s_lshl_b32 s1, s0, 7
	s_add_i32 s0, s6, s1
	s_mul_hi_i32 s0, s0, 0x2e8ba2e9
	s_lshr_b32 s7, s0, 31
	s_ashr_i32 s0, s0, 6
	s_add_i32 s0, s0, s7
	s_mul_i32 s7, s0, 0x160
	s_lshl_b32 s0, s0, 6
	s_sub_i32 s7, s1, s7
	s_ashr_i32 s1, s0, 31
	s_add_i32 s7, s6, s7
	v_or_b32_e32 v25, s0, v1
	v_lshl_add_u64 v[62:63], s[0:1], 1, v[4:5]
	s_lshl_b32 s0, s7, 5
	s_ashr_i32 s1, s0, 31
	v_or_b32_e32 v26, s0, v1
	v_or_b32_e32 v28, s0, v6
	v_or_b32_e32 v30, s0, v7
	v_or_b32_e32 v32, s0, v8
	v_lshl_add_u64 v[38:39], s[0:1], 2, v[2:3]
	v_or_b32_e32 v35, 8, v25
	v_or_b32_e32 v37, 16, v25
	v_or_b32_e32 v40, 24, v25
	v_or_b32_e32 v41, 32, v25
	v_or_b32_e32 v42, 40, v25
	v_or_b32_e32 v43, 48, v25
	v_or_b32_e32 v44, 56, v25
	v_ashrrev_i32_e32 v27, 31, v26
	v_ashrrev_i32_e32 v29, 31, v28
	v_ashrrev_i32_e32 v31, 31, v30
	v_ashrrev_i32_e32 v33, 31, v32
	v_mad_i64_i32 v[64:65], s[0:1], v25, s2, v[38:39]
	v_mad_i64_i32 v[66:67], s[0:1], v35, s2, v[38:39]
	v_mad_i64_i32 v[68:69], s[0:1], v37, s2, v[38:39]
	v_mad_i64_i32 v[70:71], s[0:1], v40, s2, v[38:39]
	v_mad_i64_i32 v[72:73], s[0:1], v41, s2, v[38:39]
	v_mad_i64_i32 v[74:75], s[0:1], v42, s2, v[38:39]
	v_mad_i64_i32 v[76:77], s[0:1], v43, s2, v[38:39]
	v_mad_i64_i32 v[78:79], s[0:1], v44, s2, v[38:39]
	v_lshlrev_b64 v[80:81], 11, v[26:27]
	v_lshlrev_b64 v[82:83], 11, v[28:29]
	v_lshlrev_b64 v[84:85], 11, v[30:31]
	v_lshlrev_b64 v[86:87], 11, v[32:33]
	global_load_dwordx4 v[26:29], v[64:65], off
	global_load_dwordx4 v[30:33], v[66:67], off
	global_load_dwordx4 v[38:41], v[68:69], off
	global_load_dwordx4 v[42:45], v[70:71], off
	global_load_dwordx4 v[46:49], v[72:73], off
	global_load_dwordx4 v[50:53], v[74:75], off
	global_load_dwordx4 v[54:57], v[76:77], off
	global_load_dwordx4 v[58:61], v[78:79], off
	v_lshl_add_u64 v[64:65], v[62:63], 0, v[80:81]
	v_lshl_add_u64 v[66:67], v[62:63], 0, v[82:83]
	v_lshl_add_u64 v[68:69], v[62:63], 0, v[84:85]
	v_lshl_add_u64 v[62:63], v[62:63], 0, v[86:87]
	s_add_i32 s6, s6, s25
	s_cmpk_gt_i32 s6, 0xdff
	s_waitcnt vmcnt(7)
	ds_write2_b32 v10, v26, v27 offset1:1
	ds_write2_b32 v10, v28, v29 offset0:2 offset1:3
	s_waitcnt vmcnt(6)
	ds_write2_b32 v11, v30, v31 offset1:1
	ds_write2_b32 v12, v32, v33 offset1:1
	s_waitcnt vmcnt(5)
	ds_write2_b32 v13, v38, v39 offset1:1
	ds_write2_b32 v14, v40, v41 offset1:1
	s_waitcnt vmcnt(4)
	ds_write2_b32 v15, v42, v43 offset1:1
	ds_write2_b32 v16, v44, v45 offset1:1
	s_waitcnt vmcnt(3)
	ds_write2_b32 v17, v46, v47 offset1:1
	ds_write2_b32 v18, v48, v49 offset1:1
	s_waitcnt vmcnt(2)
	ds_write2_b32 v19, v50, v51 offset1:1
	ds_write2_b32 v20, v52, v53 offset1:1
	s_waitcnt vmcnt(1)
	ds_write2_b32 v21, v54, v55 offset1:1
	ds_write2_b32 v22, v56, v57 offset1:1
	s_waitcnt vmcnt(0)
	ds_write2_b32 v23, v58, v59 offset1:1
	ds_write2_b32 v24, v60, v61 offset1:1
	s_waitcnt lgkmcnt(0)
	ds_read2_b32 v[26:27], v9 offset0:33 offset1:41
	ds_read2_b32 v[28:29], v9 offset1:8
	ds_read2_b32 v[30:31], v9 offset0:66 offset1:74
	ds_read2_b32 v[32:33], v9 offset0:99 offset1:107
	ds_read2_b32 v[38:39], v9 offset0:132 offset1:140
	ds_read2_b32 v[40:41], v9 offset0:165 offset1:173
	ds_read2_b32 v[42:43], v9 offset0:198 offset1:206
	ds_read2_b32 v[44:45], v9 offset0:231 offset1:239
	ds_read2_b32 v[46:47], v9 offset0:49 offset1:57
	ds_read2_b32 v[48:49], v9 offset0:16 offset1:24
	ds_read2_b32 v[50:51], v9 offset0:82 offset1:90
	ds_read2_b32 v[52:53], v9 offset0:115 offset1:123
	ds_read2_b32 v[54:55], v9 offset0:148 offset1:156
	ds_read2_b32 v[56:57], v9 offset0:181 offset1:189
	ds_read2_b32 v[58:59], v9 offset0:214 offset1:222
	ds_read2_b32 v[60:61], v9 offset0:247 offset1:255
	s_waitcnt lgkmcnt(14)
	v_bfe_u32 v25, v28, 16, 1
	s_waitcnt lgkmcnt(13)
	v_bfe_u32 v37, v30, 16, 1
	s_waitcnt lgkmcnt(12)
	v_bfe_u32 v70, v32, 16, 1
	s_waitcnt lgkmcnt(11)
	v_bfe_u32 v71, v38, 16, 1
	s_waitcnt lgkmcnt(9)
	v_bfe_u32 v73, v42, 16, 1
	v_bfe_u32 v35, v26, 16, 1
	v_bfe_u32 v72, v40, 16, 1
	s_waitcnt lgkmcnt(8)
	v_bfe_u32 v74, v44, 16, 1
	v_bfe_u32 v75, v29, 16, 1
	v_bfe_u32 v76, v27, 16, 1
	v_bfe_u32 v77, v31, 16, 1
	v_bfe_u32 v78, v33, 16, 1
	v_bfe_u32 v79, v39, 16, 1
	v_bfe_u32 v80, v41, 16, 1
	v_bfe_u32 v81, v43, 16, 1
	v_bfe_u32 v82, v45, 16, 1
	s_waitcnt lgkmcnt(6)
	v_bfe_u32 v83, v48, 16, 1
	v_bfe_u32 v84, v46, 16, 1
	s_waitcnt lgkmcnt(5)
	v_bfe_u32 v85, v50, 16, 1
	s_waitcnt lgkmcnt(4)
	v_bfe_u32 v86, v52, 16, 1
	s_waitcnt lgkmcnt(3)
	v_bfe_u32 v87, v54, 16, 1
	s_waitcnt lgkmcnt(2)
	v_bfe_u32 v88, v56, 16, 1
	s_waitcnt lgkmcnt(1)
	v_bfe_u32 v89, v58, 16, 1
	v_bfe_u32 v91, v49, 16, 1
	v_bfe_u32 v93, v51, 16, 1
	v_bfe_u32 v95, v55, 16, 1
	v_bfe_u32 v96, v57, 16, 1
	v_bfe_u32 v97, v59, 16, 1
	v_add3_u32 v25, v28, v25, s3
	v_add3_u32 v28, v30, v37, s3
	v_add3_u32 v30, v32, v70, s3
	v_add3_u32 v32, v38, v71, s3
	v_add3_u32 v37, v42, v73, s3
	s_waitcnt lgkmcnt(0)
	v_bfe_u32 v90, v60, 16, 1
	v_bfe_u32 v92, v47, 16, 1
	v_bfe_u32 v94, v53, 16, 1
	v_bfe_u32 v98, v61, 16, 1
	v_add3_u32 v26, v26, v35, s3
	v_add3_u32 v35, v40, v72, s3
	v_add3_u32 v38, v44, v74, s3
	v_add3_u32 v29, v29, v75, s3
	v_add3_u32 v40, v27, v76, s3
	v_add3_u32 v27, v31, v77, s3
	v_add3_u32 v31, v33, v78, s3
	v_add3_u32 v33, v39, v79, s3
	v_add3_u32 v39, v41, v80, s3
	v_add3_u32 v41, v43, v81, s3
	v_add3_u32 v42, v45, v82, s3
	v_add3_u32 v43, v48, v83, s3
	v_add3_u32 v44, v46, v84, s3
	v_add3_u32 v45, v50, v85, s3
	v_add3_u32 v46, v52, v86, s3
	v_add3_u32 v48, v54, v87, s3
	v_add3_u32 v50, v56, v88, s3
	v_add3_u32 v52, v58, v89, s3
	v_add3_u32 v49, v49, v91, s3
	v_add3_u32 v51, v51, v93, s3
	v_add3_u32 v55, v55, v95, s3
	v_add3_u32 v56, v57, v96, s3
	v_add3_u32 v57, v59, v97, s3
	v_lshrrev_b32_e32 v25, 16, v25
	v_lshrrev_b32_e32 v28, 16, v28
	v_lshrrev_b32_e32 v32, 16, v32
	v_lshrrev_b32_e32 v37, 16, v37
	v_add3_u32 v54, v60, v90, s3
	v_add3_u32 v47, v47, v92, s3
	v_add3_u32 v53, v53, v94, s3
	v_add3_u32 v58, v61, v98, s3
	v_lshrrev_b32_e32 v59, 16, v29
	v_lshrrev_b32_e32 v60, 16, v27
	v_lshrrev_b32_e32 v33, 16, v33
	v_lshrrev_b32_e32 v41, 16, v41
	v_lshrrev_b32_e32 v43, 16, v43
	v_lshrrev_b32_e32 v45, 16, v45
	v_lshrrev_b32_e32 v48, 16, v48
	v_lshrrev_b32_e32 v52, 16, v52
	v_lshrrev_b32_e32 v49, 16, v49
	v_lshrrev_b32_e32 v51, 16, v51
	v_lshrrev_b32_e32 v55, 16, v55
	v_lshrrev_b32_e32 v57, 16, v57
	v_and_or_b32 v26, v26, s5, v25
	v_and_or_b32 v27, v30, s5, v28
	v_and_or_b32 v28, v35, s5, v32
	v_and_or_b32 v29, v38, s5, v37
	v_and_or_b32 v30, v40, s5, v59
	v_and_or_b32 v31, v31, s5, v60
	v_and_or_b32 v32, v39, s5, v33
	v_and_or_b32 v33, v42, s5, v41
	v_and_or_b32 v38, v44, s5, v43
	v_and_or_b32 v39, v46, s5, v45
	v_and_or_b32 v40, v50, s5, v48
	v_and_or_b32 v41, v54, s5, v52
	v_and_or_b32 v42, v47, s5, v49
	v_and_or_b32 v43, v53, s5, v51
	v_and_or_b32 v44, v56, s5, v55
	v_and_or_b32 v45, v58, s5, v57
	global_store_dwordx4 v[64:65], v[26:29], off nt
	global_store_dwordx4 v[66:67], v[30:33], off nt
	global_store_dwordx4 v[68:69], v[38:41], off nt
	global_store_dwordx4 v[62:63], v[42:45], off nt
	s_waitcnt lgkmcnt(0)
	s_cbranch_scc0 .LBB0_41

.LBB0_44:
	s_add_i32 s4, s4, s0
	s_add_u32 s6, s6, s8
	s_addc_u32 s7, s7, s9
	s_add_u32 s10, s10, s18
	s_addc_u32 s11, s11, s19
	s_add_u32 s20, s20, s22
	s_addc_u32 s21, s21, s23
	s_add_u32 s16, s16, s22
	v_bfe_u32 v3, v4, 16, 1
	s_addc_u32 s17, s17, s23
	v_add3_u32 v3, v4, v3, s28
	v_bfe_u32 v4, v5, 16, 1
	s_add_u32 s14, s14, s18
	v_lshrrev_b32_e32 v3, 16, v3
	v_add3_u32 v4, v5, v4, s28
	s_addc_u32 s15, s15, s19
	v_lshl_add_u64 v[6:7], s[2:3], 1, v[40:41]
	v_and_or_b32 v3, v4, s5, v3
	s_cmp_lt_i32 s4, s62
	global_store_dwordx2 v[6:7], v[2:3], off offset:1536 nt
	s_cbranch_scc0 .Lmy_p0_bdisp
.LBB0_45:
	s_add_i32 s26, s4, s25
	s_mov_b64 s[2:3], -1
	s_cmpk_gt_i32 s26, 0x7fff
	v_lshl_add_u64 v[10:11], s[10:11], 0, v[34:35]
	v_lshl_add_u64 v[44:45], s[20:21], 0, v[36:37]
	s_cbranch_scc0 .LBB0_47
	global_load_dwordx4 v[6:9], v[10:11], off
	global_load_dwordx4 v[12:15], v[10:11], off offset:1024
	global_load_dwordx4 v[2:5], v[10:11], off offset:3072
	global_load_dwordx4 v[16:19], v[10:11], off offset:2048
	global_load_dwordx4 v[20:23], v[38:39], off
	v_cmp_lt_i32_e32 vcc, v46, v43
	s_waitcnt vmcnt(4)
	v_pk_mul_f32 v[26:27], v[6:7], v[6:7]
	v_cndmask_b32_e32 v24, v1, v46, vcc
	v_lshlrev_b32_e32 v53, 2, v24
	v_pk_mul_f32 v[24:25], v[8:9], v[8:9]
	s_waitcnt vmcnt(3)
	v_pk_mul_f32 v[28:29], v[14:15], v[14:15]
	v_pk_mul_f32 v[30:31], v[12:13], v[12:13]
	v_pk_mov_b32 v[56:57], v[26:27], v[24:25] op_sel:[1,0]
	v_mov_b32_e32 v27, v25
	v_pk_mov_b32 v[24:25], v[30:31], v[28:29] op_sel:[1,0]
	v_mov_b32_e32 v31, v29
	s_waitcnt vmcnt(2)
	v_mul_f32_e32 v55, v2, v2
	s_waitcnt vmcnt(1)
	v_mul_f32_e32 v32, v17, v17
	v_mul_f32_e32 v54, v19, v19
	v_pk_add_f32 v[26:27], v[56:57], v[26:27]
	v_pk_add_f32 v[24:25], v[24:25], v[30:31]
	v_mul_f32_e32 v58, v3, v3
	v_mul_f32_e32 v59, v4, v4
	v_mul_f32_e32 v60, v5, v5
	v_pk_fma_f32 v[28:29], v[16:17], v[16:17], v[32:33] op_sel_hi:[1,1,0]
	v_pk_fma_f32 v[32:33], v[18:19], v[18:19], v[54:55] op_sel_hi:[1,1,0]
	v_pk_add_f32 v[26:27], v[26:27], v[26:27] op_sel:[0,1] op_sel_hi:[1,0]
	v_pk_add_f32 v[24:25], v[24:25], v[24:25] op_sel:[0,1] op_sel_hi:[1,0]
	v_mov_b32_e32 v29, v59
	v_mov_b32_e32 v33, v60
	v_mov_b32_e32 v27, v55
	v_mov_b32_e32 v25, v58
	v_pk_add_f32 v[28:29], v[28:29], v[32:33]
	v_pk_add_f32 v[24:25], v[26:27], v[24:25]
	v_cmp_lt_i32_e32 vcc, v47, v43
	v_pk_add_f32 v[24:25], v[24:25], v[28:29]
	s_nop 0
	v_add_f32_e32 v24, v24, v25
	ds_bpermute_b32 v25, v53, v24
	v_cndmask_b32_e32 v26, v1, v47, vcc
	v_lshlrev_b32_e32 v26, 2, v26
	v_cmp_lt_i32_e32 vcc, v48, v43
	s_waitcnt lgkmcnt(0)
	v_add_f32_e32 v24, v24, v25
	ds_bpermute_b32 v25, v26, v24
	v_cndmask_b32_e32 v26, v1, v48, vcc
	v_lshlrev_b32_e32 v26, 2, v26
	v_cmp_lt_i32_e32 vcc, v49, v43
	s_waitcnt lgkmcnt(0)
	v_add_f32_e32 v24, v24, v25
	ds_bpermute_b32 v25, v26, v24
	v_cndmask_b32_e32 v26, v1, v49, vcc
	v_lshlrev_b32_e32 v26, 2, v26
	v_cmp_lt_i32_e32 vcc, v50, v43
	s_waitcnt lgkmcnt(0)
	v_add_f32_e32 v24, v24, v25
	ds_bpermute_b32 v25, v26, v24
	v_cndmask_b32_e32 v26, v1, v50, vcc
	v_lshlrev_b32_e32 v26, 2, v26
	v_cmp_lt_i32_e32 vcc, v51, v43
	s_waitcnt lgkmcnt(0)
	v_add_f32_e32 v24, v24, v25
	ds_bpermute_b32 v25, v26, v24
	v_cndmask_b32_e32 v26, v1, v51, vcc
	v_lshlrev_b32_e32 v26, 2, v26
	s_waitcnt lgkmcnt(0)
	v_add_f32_e32 v24, v24, v25
	ds_bpermute_b32 v25, v26, v24
	s_waitcnt lgkmcnt(0)
	v_add_f32_e32 v24, v24, v25
	v_fmamk_f32 v24, v24, 0x3a800000, v42
	v_mul_f32_e32 v25, 0x4b800000, v24
	v_cmp_gt_f32_e32 vcc, s1, v24
	s_nop 1
	v_cndmask_b32_e32 v24, v24, v25, vcc
	v_rsq_f32_e32 v26, v24
	v_add_co_u32_e64 v24, s[2:3], s29, v44
	v_mul_f32_e32 v27, 0x45800000, v26
	v_cndmask_b32_e32 v26, v26, v27, vcc
	v_mul_f32_e32 v6, v6, v26
	v_mul_f32_e32 v8, v8, v26
	v_mul_f32_e32 v7, v7, v26
	v_mul_f32_e32 v9, v9, v26
	s_waitcnt vmcnt(0)
	v_mul_f32_e32 v6, v20, v6
	v_mul_f32_e32 v8, v22, v8
	v_mul_f32_e32 v7, v21, v7
	v_mul_f32_e32 v9, v23, v9
	v_bfe_u32 v20, v6, 16, 1
	v_bfe_u32 v22, v8, 16, 1
	v_bfe_u32 v21, v7, 16, 1
	v_bfe_u32 v23, v9, 16, 1
	v_add3_u32 v6, v6, v20, s28
	v_add3_u32 v8, v8, v22, s28
	v_add3_u32 v7, v7, v21, s28
	v_add3_u32 v9, v9, v23, s28
	v_lshrrev_b32_e32 v6, 16, v6
	v_lshrrev_b32_e32 v8, 16, v8
	v_addc_co_u32_e64 v25, s[2:3], 0, v45, s[2:3]
	v_and_or_b32 v6, v7, s5, v6
	v_and_or_b32 v7, v9, s5, v8
	global_store_dwordx2 v[24:25], v[6:7], off nt
	global_load_dwordx4 v[6:9], v[38:39], off offset:1024
	v_mul_f32_e32 v12, v12, v26
	v_mul_f32_e32 v14, v14, v26
	v_mul_f32_e32 v13, v13, v26
	v_mul_f32_e32 v15, v15, v26
	v_pk_mul_f32 v[2:3], v[2:3], v[26:27] op_sel_hi:[1,0]
	v_pk_mul_f32 v[4:5], v[4:5], v[26:27] op_sel_hi:[1,0]
	s_mov_b64 s[2:3], 0
	s_waitcnt vmcnt(0)
	v_mul_f32_e32 v6, v6, v12
	v_mul_f32_e32 v8, v8, v14
	v_mul_f32_e32 v7, v7, v13
	v_mul_f32_e32 v9, v9, v15
	v_bfe_u32 v12, v6, 16, 1
	v_bfe_u32 v14, v8, 16, 1
	v_bfe_u32 v13, v7, 16, 1
	v_bfe_u32 v15, v9, 16, 1
	v_add3_u32 v6, v6, v12, s28
	v_add3_u32 v8, v8, v14, s28
	v_add3_u32 v7, v7, v13, s28
	v_add3_u32 v9, v9, v15, s28
	v_lshrrev_b32_e32 v6, 16, v6
	v_lshrrev_b32_e32 v8, 16, v8
	v_and_or_b32 v6, v7, s5, v6
	v_and_or_b32 v7, v9, s5, v8
	global_store_dwordx2 v[24:25], v[6:7], off offset:512 nt
	global_load_dwordx4 v[6:9], v[38:39], off offset:2048
	v_mul_f32_e32 v12, v16, v26
	v_mul_f32_e32 v14, v18, v26
	v_mul_f32_e32 v13, v17, v26
	v_mul_f32_e32 v15, v19, v26
	s_waitcnt vmcnt(0)
	v_mul_f32_e32 v6, v6, v12
	v_mul_f32_e32 v8, v8, v14
	v_mul_f32_e32 v7, v7, v13
	v_mul_f32_e32 v9, v9, v15
	v_bfe_u32 v12, v6, 16, 1
	v_bfe_u32 v14, v8, 16, 1
	v_bfe_u32 v13, v7, 16, 1
	v_bfe_u32 v15, v9, 16, 1
	v_add3_u32 v6, v6, v12, s28
	v_add3_u32 v8, v8, v14, s28
	v_add3_u32 v7, v7, v13, s28
	v_add3_u32 v9, v9, v15, s28
	v_lshrrev_b32_e32 v6, 16, v6
	v_lshrrev_b32_e32 v8, 16, v8
	v_and_or_b32 v6, v7, s5, v6
	v_and_or_b32 v7, v9, s5, v8
	global_store_dwordx2 v[24:25], v[6:7], off offset:1024 nt
	global_load_dwordx4 v[6:9], v[38:39], off offset:3072
	s_waitcnt vmcnt(0)
	v_pk_mul_f32 v[2:3], v[6:7], v[2:3]
	s_nop 0
	v_and_b32_sdwa v7, v2, v52 dst_sel:DWORD dst_unused:UNUSED_PAD src0_sel:WORD_1 src1_sel:DWORD
	v_and_b32_sdwa v6, v3, v52 dst_sel:DWORD dst_unused:UNUSED_PAD src0_sel:WORD_1 src1_sel:DWORD
	v_add3_u32 v2, v2, v7, s28
	v_add3_u32 v3, v3, v6, s28
	v_lshrrev_b32_e32 v2, 16, v2
	v_pk_mul_f32 v[4:5], v[8:9], v[4:5]
	v_and_or_b32 v2, v3, s5, v2
.LBB0_47:
	s_andn2_b64 vcc, exec, s[2:3]
	s_mov_b64 s[2:3], s[6:7]
	s_cbranch_vccnz .LBB0_44
	global_load_dwordx4 v[30:33], v[10:11], off
	global_load_dwordx4 v[22:25], v[10:11], off offset:1024
	global_load_dwordx4 v[6:9], v[10:11], off offset:3072
	global_load_dwordx4 v[14:17], v[10:11], off offset:2048
	v_lshl_add_u64 v[54:55], s[14:15], 0, v[34:35]
	global_load_dwordx4 v[26:29], v[54:55], off
	global_load_dwordx4 v[18:21], v[54:55], off offset:1024
	global_load_dwordx4 v[2:5], v[54:55], off offset:3072
	global_load_dwordx4 v[10:13], v[54:55], off offset:2048
	v_cmp_lt_i32_e32 vcc, v46, v43
	s_ashr_i32 s27, s26, 31
	v_cndmask_b32_e32 v53, v1, v46, vcc
	v_lshlrev_b32_e32 v53, 2, v53
	v_cmp_lt_i32_e32 vcc, v47, v43
	s_waitcnt vmcnt(7)
	v_pk_mul_f32 v[58:59], v[32:33], v[32:33]
	v_pk_mul_f32 v[60:61], v[30:31], v[30:31]
	s_waitcnt vmcnt(6)
	v_pk_mul_f32 v[62:63], v[24:25], v[24:25]
	v_pk_mul_f32 v[64:65], v[22:23], v[22:23]
	s_waitcnt vmcnt(4)
	v_mul_f32_e32 v66, v15, v15
	v_mul_f32_e32 v68, v17, v17
	v_pk_mov_b32 v[70:71], v[60:61], v[58:59] op_sel:[1,0]
	v_mov_b32_e32 v61, v59
	s_waitcnt vmcnt(3)
	v_pk_mul_f32 v[58:59], v[28:29], v[28:29]
	v_pk_mul_f32 v[72:73], v[26:27], v[26:27]
	v_pk_mov_b32 v[74:75], v[64:65], v[62:63] op_sel:[1,0]
	v_mov_b32_e32 v65, v63
	s_waitcnt vmcnt(2)
	v_pk_mul_f32 v[62:63], v[20:21], v[20:21]
	v_pk_mul_f32 v[76:77], v[18:19], v[18:19]
	v_mul_f32_e32 v82, v8, v8
	v_mul_f32_e32 v83, v9, v9
	v_pk_fma_f32 v[66:67], v[14:15], v[14:15], v[66:67] op_sel_hi:[1,1,0]
	v_pk_fma_f32 v[68:69], v[16:17], v[16:17], v[68:69] op_sel_hi:[1,1,0]
	v_pk_add_f32 v[60:61], v[70:71], v[60:61]
	v_pk_mov_b32 v[70:71], v[72:73], v[58:59] op_sel:[1,0]
	v_mov_b32_e32 v73, v59
	v_pk_add_f32 v[58:59], v[74:75], v[64:65]
	v_pk_mov_b32 v[64:65], v[76:77], v[62:63] op_sel:[1,0]
	v_mov_b32_e32 v77, v63
	v_mul_f32_e32 v79, v6, v6
	v_mul_f32_e32 v81, v7, v7
	s_waitcnt vmcnt(0)
	v_mul_f32_e32 v78, v11, v11
	v_mul_f32_e32 v80, v13, v13
	v_mov_b32_e32 v67, v82
	v_mov_b32_e32 v69, v83
	v_pk_add_f32 v[70:71], v[70:71], v[72:73]
	v_pk_add_f32 v[64:65], v[64:65], v[76:77]
	v_mul_f32_e32 v84, v2, v2
	v_mul_f32_e32 v85, v3, v3
	v_mul_f32_e32 v86, v4, v4
	v_mul_f32_e32 v87, v5, v5
	v_pk_fma_f32 v[62:63], v[10:11], v[10:11], v[78:79] op_sel_hi:[1,1,0]
	v_pk_fma_f32 v[74:75], v[12:13], v[12:13], v[80:81] op_sel_hi:[1,1,0]
	v_pk_add_f32 v[60:61], v[60:61], v[60:61] op_sel:[0,1] op_sel_hi:[1,0]
	v_pk_add_f32 v[58:59], v[58:59], v[58:59] op_sel:[0,1] op_sel_hi:[1,0]
	v_pk_add_f32 v[66:67], v[66:67], v[68:69]
	v_pk_add_f32 v[68:69], v[70:71], v[70:71] op_sel:[0,1] op_sel_hi:[1,0]
	v_pk_add_f32 v[64:65], v[64:65], v[64:65] op_sel:[0,1] op_sel_hi:[1,0]
	v_mov_b32_e32 v63, v86
	v_mov_b32_e32 v75, v87
	v_mov_b32_e32 v61, v79
	v_mov_b32_e32 v59, v81
	v_mov_b32_e32 v69, v84
	v_mov_b32_e32 v65, v85
	v_pk_add_f32 v[62:63], v[62:63], v[74:75]
	v_pk_add_f32 v[58:59], v[60:61], v[58:59]
	v_pk_add_f32 v[60:61], v[68:69], v[64:65]
	v_pk_add_f32 v[58:59], v[58:59], v[66:67]
	v_pk_add_f32 v[60:61], v[60:61], v[62:63]
	v_mov_b32_e32 v63, v58
	v_mov_b32_e32 v62, v60
	v_mov_b32_e32 v58, v61
	v_pk_add_f32 v[58:59], v[62:63], v[58:59]
	ds_bpermute_b32 v61, v53, v59
	ds_bpermute_b32 v60, v53, v58
	v_cndmask_b32_e32 v53, v1, v47, vcc
	v_lshlrev_b32_e32 v53, 2, v53
	v_cmp_lt_i32_e32 vcc, v48, v43
	s_waitcnt lgkmcnt(0)
	v_pk_add_f32 v[58:59], v[58:59], v[60:61]
	ds_bpermute_b32 v61, v53, v59
	ds_bpermute_b32 v60, v53, v58
	v_cndmask_b32_e32 v53, v1, v48, vcc
	v_lshlrev_b32_e32 v53, 2, v53
	v_cmp_lt_i32_e32 vcc, v49, v43
	s_waitcnt lgkmcnt(0)
	v_pk_add_f32 v[58:59], v[58:59], v[60:61]
	ds_bpermute_b32 v61, v53, v59
	ds_bpermute_b32 v60, v53, v58
	v_cndmask_b32_e32 v53, v1, v49, vcc
	v_lshlrev_b32_e32 v53, 2, v53
	v_cmp_lt_i32_e32 vcc, v50, v43
	s_waitcnt lgkmcnt(0)
	v_pk_add_f32 v[58:59], v[58:59], v[60:61]
	ds_bpermute_b32 v61, v53, v59
	ds_bpermute_b32 v60, v53, v58
	v_cndmask_b32_e32 v53, v1, v50, vcc
	v_lshlrev_b32_e32 v53, 2, v53
	v_cmp_lt_i32_e32 vcc, v51, v43
	s_waitcnt lgkmcnt(0)
	v_pk_add_f32 v[58:59], v[58:59], v[60:61]
	ds_bpermute_b32 v61, v53, v59
	ds_bpermute_b32 v60, v53, v58
	v_cndmask_b32_e32 v53, v1, v51, vcc
	v_lshlrev_b32_e32 v53, 2, v53
	s_waitcnt lgkmcnt(0)
	v_pk_add_f32 v[58:59], v[58:59], v[60:61]
	ds_bpermute_b32 v61, v53, v59
	ds_bpermute_b32 v60, v53, v58
	s_waitcnt lgkmcnt(0)
	v_pk_add_f32 v[58:59], v[58:59], v[60:61]
	s_nop 0
	v_pk_fma_f32 v[58:59], v[58:59], s[24:25], v[42:43] op_sel_hi:[1,0,0]
	s_nop 0
	v_mul_f32_e32 v53, 0x4b800000, v59
	v_cmp_gt_f32_e32 vcc, s1, v59
	v_mul_f32_e32 v60, 0x4b800000, v58
	v_cmp_gt_f32_e64 s[2:3], s1, v58
	v_cndmask_b32_e32 v53, v59, v53, vcc
	v_rsq_f32_e32 v53, v53
	v_cndmask_b32_e64 v58, v58, v60, s[2:3]
	v_rsq_f32_e32 v60, v58
	v_lshl_add_u64 v[58:59], s[16:17], 0, v[36:37]
	v_mul_f32_e32 v61, 0x45800000, v53
	v_cndmask_b32_e32 v53, v53, v61, vcc
	v_mul_f32_e32 v30, v30, v53
	v_mul_f32_e32 v32, v32, v53
	v_mul_f32_e32 v31, v31, v53
	v_mul_f32_e32 v33, v33, v53
	v_mul_f32_e32 v30, v88, v30
	v_mul_f32_e32 v32, v90, v32
	v_mul_f32_e32 v62, 0x45800000, v60
	v_mul_f32_e32 v31, v89, v31
	v_mul_f32_e32 v33, v91, v33
	v_bfe_u32 v61, v30, 16, 1
	v_bfe_u32 v63, v32, 16, 1
	v_cndmask_b32_e64 v60, v60, v62, s[2:3]
	v_bfe_u32 v62, v31, 16, 1
	v_bfe_u32 v64, v33, 16, 1
	v_add3_u32 v30, v30, v61, s28
	v_add3_u32 v32, v32, v63, s28
	v_add3_u32 v31, v31, v62, s28
	v_add3_u32 v33, v33, v64, s28
	v_lshrrev_b32_e32 v30, 16, v30
	v_lshrrev_b32_e32 v32, 16, v32
	v_and_or_b32 v30, v31, s5, v30
	v_and_or_b32 v31, v33, s5, v32
	v_add_co_u32_e32 v32, vcc, s29, v44
	v_mul_f32_e32 v26, v26, v60
	s_nop 0
	v_addc_co_u32_e32 v33, vcc, 0, v45, vcc
	v_mul_f32_e32 v26, v88, v26
	v_mul_f32_e32 v27, v27, v60
	global_store_dwordx2 v[32:33], v[30:31], off nt
	v_mul_f32_e32 v27, v89, v27
	v_bfe_u32 v30, v26, 16, 1
	v_add3_u32 v26, v26, v30, s28
	v_bfe_u32 v30, v27, 16, 1
	v_lshrrev_b32_e32 v26, 16, v26
	v_add3_u32 v27, v27, v30, s28
	v_and_or_b32 v26, v27, s5, v26
	v_mul_f32_e32 v27, v28, v60
	v_mul_f32_e32 v27, v90, v27
	v_mul_f32_e32 v28, v29, v60
	v_mul_f32_e32 v28, v91, v28
	v_bfe_u32 v29, v27, 16, 1
	v_add3_u32 v27, v27, v29, s28
	v_bfe_u32 v29, v28, 16, 1
	v_lshrrev_b32_e32 v27, 16, v27
	v_add3_u32 v28, v28, v29, s28
	v_add_co_u32_e32 v30, vcc, s29, v58
	v_and_or_b32 v27, v28, s5, v27
	s_nop 0
	v_addc_co_u32_e32 v31, vcc, 0, v59, vcc
	global_store_dwordx2 v[30:31], v[26:27], off nt
	v_mul_f32_e32 v22, v22, v53
	v_mul_f32_e32 v24, v24, v53
	v_mul_f32_e32 v23, v23, v53
	v_mul_f32_e32 v25, v25, v53
	v_mul_f32_e32 v18, v18, v60
	v_mul_f32_e32 v19, v19, v60
	v_mul_f32_e32 v20, v20, v60
	v_mul_f32_e32 v21, v21, v60
	v_mul_f32_e32 v14, v14, v53
	v_mul_f32_e32 v16, v16, v53
	v_mul_f32_e32 v15, v15, v53
	v_mul_f32_e32 v17, v17, v53
	v_mul_f32_e32 v10, v10, v60
	v_mul_f32_e32 v11, v11, v60
	v_mul_f32_e32 v12, v12, v60
	v_mul_f32_e32 v13, v13, v60
	v_mul_f32_e32 v6, v6, v53
	v_mul_f32_e32 v8, v8, v53
	v_pk_mul_f32 v[2:3], v[2:3], v[60:61] op_sel_hi:[1,0]
	v_mul_f32_e32 v7, v7, v53
	v_mul_f32_e32 v9, v9, v53
	v_pk_mul_f32 v[4:5], v[4:5], v[60:61] op_sel_hi:[1,0]
	s_lshl_b64 s[2:3], s[26:27], 10
	v_mul_f32_e32 v22, v22, v92
	v_mul_f32_e32 v24, v24, v94
	v_mul_f32_e32 v23, v23, v93
	v_mul_f32_e32 v25, v25, v95
	v_mul_f32_e32 v18, v92, v18
	v_mul_f32_e32 v19, v93, v19
	v_mul_f32_e32 v20, v94, v20
	v_bfe_u32 v26, v22, 16, 1
	v_bfe_u32 v28, v24, 16, 1
	v_mul_f32_e32 v21, v95, v21
	v_bfe_u32 v27, v23, 16, 1
	v_bfe_u32 v29, v25, 16, 1
	v_bfe_u32 v44, v18, 16, 1
	v_bfe_u32 v45, v19, 16, 1
	v_bfe_u32 v54, v20, 16, 1
	v_add3_u32 v22, v22, v26, s28
	v_add3_u32 v24, v24, v28, s28
	v_bfe_u32 v55, v21, 16, 1
	v_add3_u32 v23, v23, v27, s28
	v_add3_u32 v25, v25, v29, s28
	v_add3_u32 v18, v18, v44, s28
	v_add3_u32 v26, v19, v45, s28
	v_add3_u32 v19, v20, v54, s28
	v_lshrrev_b32_e32 v20, 16, v22
	v_lshrrev_b32_e32 v22, 16, v24
	v_add3_u32 v21, v21, v55, s28
	v_lshrrev_b32_e32 v24, 16, v18
	v_lshrrev_b32_e32 v27, 16, v19
	v_and_or_b32 v18, v23, s5, v20
	v_and_or_b32 v19, v25, s5, v22
	v_and_or_b32 v20, v26, s5, v24
	v_and_or_b32 v21, v21, s5, v27
	global_store_dwordx2 v[32:33], v[18:19], off offset:512 nt
	global_store_dwordx2 v[30:31], v[20:21], off offset:512 nt
	v_mul_f32_e32 v14, v14, v96
	v_mul_f32_e32 v16, v16, v98
	v_mul_f32_e32 v15, v15, v97
	v_mul_f32_e32 v17, v17, v99
	v_mul_f32_e32 v10, v96, v10
	v_mul_f32_e32 v11, v97, v11
	v_mul_f32_e32 v12, v98, v12
	v_bfe_u32 v18, v14, 16, 1
	v_bfe_u32 v20, v16, 16, 1
	v_mul_f32_e32 v13, v99, v13
	v_bfe_u32 v19, v15, 16, 1
	v_bfe_u32 v21, v17, 16, 1
	v_bfe_u32 v22, v10, 16, 1
	v_bfe_u32 v23, v11, 16, 1
	v_bfe_u32 v24, v12, 16, 1
	v_add3_u32 v14, v14, v18, s28
	v_add3_u32 v16, v16, v20, s28
	v_bfe_u32 v25, v13, 16, 1
	v_add3_u32 v15, v15, v19, s28
	v_add3_u32 v17, v17, v21, s28
	v_add3_u32 v10, v10, v22, s28
	v_add3_u32 v18, v11, v23, s28
	v_add3_u32 v11, v12, v24, s28
	v_lshrrev_b32_e32 v12, 16, v14
	v_lshrrev_b32_e32 v14, 16, v16
	v_add3_u32 v13, v13, v25, s28
	v_lshrrev_b32_e32 v16, 16, v10
	v_lshrrev_b32_e32 v19, 16, v11
	v_and_or_b32 v10, v15, s5, v12
	v_and_or_b32 v11, v17, s5, v14
	v_and_or_b32 v12, v18, s5, v16
	v_and_or_b32 v13, v13, s5, v19
	global_store_dwordx2 v[32:33], v[10:11], off offset:1024 nt
	global_store_dwordx2 v[30:31], v[12:13], off offset:1024 nt
	v_mul_f32_e32 v6, v6, v100
	v_mul_f32_e32 v8, v8, v102
	v_pk_mul_f32 v[2:3], v[2:3], v[100:101]
	v_mul_f32_e32 v7, v7, v101
	v_mul_f32_e32 v9, v9, v103
	v_bfe_u32 v10, v6, 16, 1
	v_bfe_u32 v14, v8, 16, 1
	v_and_b32_sdwa v17, v2, v52 dst_sel:DWORD dst_unused:UNUSED_PAD src0_sel:WORD_1 src1_sel:DWORD
	v_bfe_u32 v11, v7, 16, 1
	v_bfe_u32 v15, v9, 16, 1
	v_and_b32_sdwa v16, v3, v52 dst_sel:DWORD dst_unused:UNUSED_PAD src0_sel:WORD_1 src1_sel:DWORD
	v_add3_u32 v6, v6, v10, s28
	v_add3_u32 v8, v8, v14, s28
	v_add3_u32 v2, v2, v17, s28
	v_add3_u32 v7, v7, v11, s28
	v_add3_u32 v9, v9, v15, s28
	v_add3_u32 v3, v3, v16, s28
	v_lshrrev_b32_e32 v6, 16, v6
	v_lshrrev_b32_e32 v8, 16, v8
	v_lshrrev_b32_e32 v2, 16, v2
	v_and_or_b32 v6, v7, s5, v6
	v_and_or_b32 v7, v9, s5, v8
	v_and_or_b32 v2, v3, s5, v2
	v_pk_mul_f32 v[4:5], v[4:5], v[102:103]
	global_store_dwordx2 v[32:33], v[6:7], off offset:1536 nt
	s_branch .LBB0_44

.LBB0_487:
	s_or_b64 exec, exec, s[0:1]
	v_add_f32_e32 v2, v10, v11
	v_fmamk_f32 v2, v2, 0x3c000000, v205
	v_mul_f32_e32 v10, 0x4b800000, v2
	v_cmp_gt_f32_e32 vcc, s53, v2
	s_lshl_b32 s10, s10, 1
	v_mov_b32_e32 v171, v3
	v_cndmask_b32_e32 v2, v2, v10, vcc
	v_rsq_f32_e32 v2, v2
	v_lshl_add_u64 v[10:11], v[116:117], 1, s[24:25]
	v_lshl_add_u64 v[10:11], v[10:11], 0, s[10:11]
	ds_read_b128 v[74:77], v201 offset:32
	v_mul_f32_e32 v70, 0x45800000, v2
	v_cndmask_b32_e32 v2, v2, v70, vcc
	ds_read_b128 v[70:73], v201
	v_mul_f32_e32 v2, 0x3f4ccccd, v2
	v_lshl_add_u64 v[78:79], v[10:11], 0, v[170:171]
	s_waitcnt lgkmcnt(0)
	v_pk_mul_f32 v[10:11], v[20:21], v[70:71]
	s_nop 0
	v_pk_mul_f32 v[10:11], v[2:3], v[10:11] op_sel_hi:[0,1]
	v_cvt_pk_bf16_f32 v20, v10, v11
	v_pk_mul_f32 v[10:11], v[22:23], v[72:73]
	s_nop 0
	v_pk_mul_f32 v[10:11], v[2:3], v[10:11] op_sel_hi:[0,1]
	v_cvt_pk_bf16_f32 v21, v10, v11
	v_pk_mul_f32 v[10:11], v[24:25], v[74:75]
	s_nop 0
	v_pk_mul_f32 v[10:11], v[2:3], v[10:11] op_sel_hi:[0,1]
	v_cvt_pk_bf16_f32 v22, v10, v11
	v_pk_mul_f32 v[10:11], v[26:27], v[76:77]
	ds_read_b128 v[24:27], v201 offset:64
	v_pk_mul_f32 v[10:11], v[2:3], v[10:11] op_sel_hi:[0,1]
	v_cvt_pk_bf16_f32 v23, v10, v11
	v_permlane32_swap_b32_e32 v20, v22
	s_nop 0
	v_permlane32_swap_b32_e32 v21, v23
	global_store_dwordx4 v[78:79], v[20:23], off nt
	ds_read_b128 v[20:23], v201 offset:96
	s_waitcnt lgkmcnt(1)
	v_pk_mul_f32 v[10:11], v[30:31], v[24:25]
	s_nop 0
	v_pk_mul_f32 v[10:11], v[2:3], v[10:11] op_sel_hi:[0,1]
	v_cvt_pk_bf16_f32 v24, v10, v11
	v_pk_mul_f32 v[10:11], v[28:29], v[26:27]
	s_nop 0
	v_pk_mul_f32 v[10:11], v[2:3], v[10:11] op_sel_hi:[0,1]
	v_cvt_pk_bf16_f32 v25, v10, v11
	s_waitcnt lgkmcnt(0)
	v_pk_mul_f32 v[10:11], v[32:33], v[20:21]
	s_nop 0
	v_pk_mul_f32 v[10:11], v[2:3], v[10:11] op_sel_hi:[0,1]
	v_cvt_pk_bf16_f32 v26, v10, v11
	v_pk_mul_f32 v[10:11], v[34:35], v[22:23]
	ds_read_b128 v[20:23], v201 offset:128
	v_pk_mul_f32 v[10:11], v[2:3], v[10:11] op_sel_hi:[0,1]
	v_cvt_pk_bf16_f32 v27, v10, v11
	v_permlane32_swap_b32_e32 v24, v26
	s_nop 0
	v_permlane32_swap_b32_e32 v25, v27
	global_store_dwordx4 v[78:79], v[24:27], off offset:32 nt
	ds_read_b128 v[24:27], v201 offset:160
	s_waitcnt lgkmcnt(1)
	v_pk_mul_f32 v[10:11], v[46:47], v[20:21]
	s_nop 0
	v_pk_mul_f32 v[10:11], v[2:3], v[10:11] op_sel_hi:[0,1]
	v_cvt_pk_bf16_f32 v20, v10, v11
	v_pk_mul_f32 v[10:11], v[44:45], v[22:23]
	s_nop 0
	v_pk_mul_f32 v[10:11], v[2:3], v[10:11] op_sel_hi:[0,1]
	v_cvt_pk_bf16_f32 v21, v10, v11
	s_waitcnt lgkmcnt(0)
	v_pk_mul_f32 v[10:11], v[48:49], v[24:25]
	s_nop 0
	v_pk_mul_f32 v[10:11], v[2:3], v[10:11] op_sel_hi:[0,1]
	v_cvt_pk_bf16_f32 v22, v10, v11
	v_pk_mul_f32 v[10:11], v[50:51], v[26:27]
	ds_read_b128 v[24:27], v201 offset:192
	v_pk_mul_f32 v[10:11], v[2:3], v[10:11] op_sel_hi:[0,1]
	v_cvt_pk_bf16_f32 v23, v10, v11
	v_permlane32_swap_b32_e32 v20, v22
	s_nop 0
	v_permlane32_swap_b32_e32 v21, v23
	global_store_dwordx4 v[78:79], v[20:23], off offset:64 nt
	ds_read_b128 v[20:23], v201 offset:224
	s_waitcnt lgkmcnt(1)
	v_pk_mul_f32 v[10:11], v[68:69], v[24:25]
	s_nop 0
	v_pk_mul_f32 v[10:11], v[2:3], v[10:11] op_sel_hi:[0,1]
	v_cvt_pk_bf16_f32 v24, v10, v11
	v_pk_mul_f32 v[10:11], v[64:65], v[26:27]
	s_nop 0
	v_pk_mul_f32 v[10:11], v[2:3], v[10:11] op_sel_hi:[0,1]
	v_cvt_pk_bf16_f32 v25, v10, v11
	s_waitcnt lgkmcnt(0)
	v_pk_mul_f32 v[10:11], v[60:61], v[20:21]
	s_nop 0
	v_pk_mul_f32 v[10:11], v[2:3], v[10:11] op_sel_hi:[0,1]
	v_cvt_pk_bf16_f32 v26, v10, v11
	v_pk_mul_f32 v[10:11], v[62:63], v[22:23]
	ds_read_b128 v[20:23], v201 offset:256
	v_pk_mul_f32 v[10:11], v[2:3], v[10:11] op_sel_hi:[0,1]
	v_cvt_pk_bf16_f32 v27, v10, v11
	v_permlane32_swap_b32_e32 v24, v26
	s_nop 0
	v_permlane32_swap_b32_e32 v25, v27
	global_store_dwordx4 v[78:79], v[24:27], off offset:96 nt
	ds_read_b128 v[24:27], v201 offset:288
	s_waitcnt lgkmcnt(1)
	v_pk_mul_f32 v[10:11], v[66:67], v[20:21]
	s_nop 0
	v_pk_mul_f32 v[10:11], v[2:3], v[10:11] op_sel_hi:[0,1]
	v_cvt_pk_bf16_f32 v20, v10, v11
	v_pk_mul_f32 v[10:11], v[56:57], v[22:23]
	s_nop 0
	v_pk_mul_f32 v[10:11], v[2:3], v[10:11] op_sel_hi:[0,1]
	v_cvt_pk_bf16_f32 v21, v10, v11
	s_waitcnt lgkmcnt(0)
	v_pk_mul_f32 v[10:11], v[52:53], v[24:25]
	s_nop 0
	v_pk_mul_f32 v[10:11], v[2:3], v[10:11] op_sel_hi:[0,1]
	v_cvt_pk_bf16_f32 v22, v10, v11
	v_pk_mul_f32 v[10:11], v[54:55], v[26:27]
	ds_read_b128 v[24:27], v201 offset:320
	v_pk_mul_f32 v[10:11], v[2:3], v[10:11] op_sel_hi:[0,1]
	v_cvt_pk_bf16_f32 v23, v10, v11
	v_permlane32_swap_b32_e32 v20, v22
	s_nop 0
	v_permlane32_swap_b32_e32 v21, v23
	global_store_dwordx4 v[78:79], v[20:23], off offset:128 nt
	ds_read_b128 v[20:23], v201 offset:352
	s_waitcnt lgkmcnt(1)
	v_pk_mul_f32 v[10:11], v[58:59], v[24:25]
	s_nop 0
	v_pk_mul_f32 v[10:11], v[2:3], v[10:11] op_sel_hi:[0,1]
	v_cvt_pk_bf16_f32 v24, v10, v11
	v_pk_mul_f32 v[10:11], v[40:41], v[26:27]
	s_nop 0
	v_pk_mul_f32 v[10:11], v[2:3], v[10:11] op_sel_hi:[0,1]
	v_cvt_pk_bf16_f32 v25, v10, v11
	s_waitcnt lgkmcnt(0)
	v_pk_mul_f32 v[10:11], v[36:37], v[20:21]
	s_nop 0
	v_pk_mul_f32 v[10:11], v[2:3], v[10:11] op_sel_hi:[0,1]
	v_cvt_pk_bf16_f32 v26, v10, v11
	v_pk_mul_f32 v[10:11], v[38:39], v[22:23]
	s_nop 0
	v_permlane32_swap_b32_e32 v24, v26
	v_pk_mul_f32 v[10:11], v[2:3], v[10:11] op_sel_hi:[0,1]
	v_cvt_pk_bf16_f32 v27, v10, v11
	s_nop 1
	v_permlane32_swap_b32_e32 v25, v27
	ds_read_b128 v[20:23], v201 offset:384
	global_store_dwordx4 v[78:79], v[24:27], off offset:160 nt
	ds_read_b128 v[24:27], v201 offset:416
	s_waitcnt lgkmcnt(1)
	v_pk_mul_f32 v[10:11], v[42:43], v[20:21]
	v_pk_mul_f32 v[16:17], v[16:17], v[22:23]
	s_waitcnt lgkmcnt(0)
	v_pk_mul_f32 v[12:13], v[12:13], v[24:25]
	v_pk_mul_f32 v[14:15], v[14:15], v[26:27]
	v_pk_mul_f32 v[10:11], v[2:3], v[10:11] op_sel_hi:[0,1]
	v_pk_mul_f32 v[16:17], v[2:3], v[16:17] op_sel_hi:[0,1]
	v_pk_mul_f32 v[12:13], v[2:3], v[12:13] op_sel_hi:[0,1]
	v_pk_mul_f32 v[14:15], v[2:3], v[14:15] op_sel_hi:[0,1]
	v_cvt_pk_bf16_f32 v10, v10, v11
	v_cvt_pk_bf16_f32 v11, v16, v17
	v_cvt_pk_bf16_f32 v12, v12, v13
	v_cvt_pk_bf16_f32 v13, v14, v15
	s_nop 0
	v_permlane32_swap_b32_e32 v10, v12
	v_permlane32_swap_b32_e32 v11, v13
	ds_read_b128 v[14:17], v201 offset:448
	global_store_dwordx4 v[78:79], v[10:13], off offset:192 nt
	ds_read_b128 v[10:13], v201 offset:480
	s_waitcnt lgkmcnt(1)
	v_pk_mul_f32 v[14:15], v[18:19], v[14:15]
	v_pk_mul_f32 v[8:9], v[8:9], v[16:17]
	s_waitcnt lgkmcnt(0)
	v_pk_mul_f32 v[4:5], v[4:5], v[10:11]
	v_pk_mul_f32 v[14:15], v[2:3], v[14:15] op_sel_hi:[0,1]
	v_pk_mul_f32 v[4:5], v[2:3], v[4:5] op_sel_hi:[0,1]
	v_cvt_pk_bf16_f32 v16, v4, v5
	v_pk_mul_f32 v[4:5], v[6:7], v[12:13]
	v_pk_mul_f32 v[8:9], v[2:3], v[8:9] op_sel_hi:[0,1]
	v_pk_mul_f32 v[4:5], v[2:3], v[4:5] op_sel_hi:[0,1]
	v_cvt_pk_bf16_f32 v14, v14, v15
	v_cvt_pk_bf16_f32 v15, v8, v9
	v_cvt_pk_bf16_f32 v17, v4, v5
	v_permlane32_swap_b32_e32 v14, v16
	s_nop 0
	v_permlane32_swap_b32_e32 v15, v17
	global_store_dwordx4 v[78:79], v[14:17], off offset:224 nt

.LBB0_550:
	s_cmpk_gt_u32 s6, 0x9ff
	s_cbranch_scc0 .LBB0_576
	s_cmpk_gt_u32 s6, 0xdff
	s_cbranch_scc0 .LBB0_573
	s_cmpk_gt_u32 s6, 0xfff
	s_cbranch_scc0 .LBB0_570
	s_lshl_b32 s4, s6, 5
	s_cmpk_gt_u32 s6, 0x17ff
	s_cbranch_scc0 .LBB0_555
	s_lshl_b32 s0, s6, 1
	s_and_b32 s0, s0, 0xfffffc0
	s_addk_i32 s0, 0xd000
	s_and_b32 s5, s4, 0x3e0
	v_or_b32_e32 v38, s0, v68
	s_lshl_b32 s12, s5, 2
	v_lshl_add_u64 v[30:31], v[40:41], 0, s[12:13]
	v_lshlrev_b64 v[2:3], 12, v[38:39]
	v_lshl_add_u64 v[10:11], v[30:31], 0, v[2:3]
	v_or_b32_e32 v2, 8, v38
	v_mov_b32_e32 v3, v39
	v_lshlrev_b64 v[2:3], 12, v[2:3]
	v_lshl_add_u64 v[12:13], v[30:31], 0, v[2:3]
	global_load_dwordx4 v[2:5], v[10:11], off
	global_load_dwordx4 v[6:9], v[12:13], off
	v_or_b32_e32 v10, 16, v38
	v_mov_b32_e32 v11, v39
	v_lshlrev_b64 v[10:11], 12, v[10:11]
	v_lshl_add_u64 v[18:19], v[30:31], 0, v[10:11]
	v_or_b32_e32 v10, 24, v38
	v_mov_b32_e32 v11, v39
	v_lshlrev_b64 v[10:11], 12, v[10:11]
	v_lshl_add_u64 v[20:21], v[30:31], 0, v[10:11]
	global_load_dwordx4 v[10:13], v[18:19], off
	global_load_dwordx4 v[14:17], v[20:21], off
	v_or_b32_e32 v18, 32, v38
	v_mov_b32_e32 v19, v39
	v_lshlrev_b64 v[18:19], 12, v[18:19]
	v_lshl_add_u64 v[26:27], v[30:31], 0, v[18:19]
	v_or_b32_e32 v18, 40, v38
	v_mov_b32_e32 v19, v39
	v_lshlrev_b64 v[18:19], 12, v[18:19]
	v_lshl_add_u64 v[28:29], v[30:31], 0, v[18:19]
	global_load_dwordx4 v[18:21], v[26:27], off
	global_load_dwordx4 v[22:25], v[28:29], off
	v_or_b32_e32 v26, 48, v38
	v_mov_b32_e32 v27, v39
	v_lshlrev_b64 v[26:27], 12, v[26:27]
	v_lshl_add_u64 v[26:27], v[30:31], 0, v[26:27]
	v_or_b32_e32 v38, 56, v38
	global_load_dwordx4 v[26:29], v[26:27], off
	v_lshlrev_b64 v[32:33], 12, v[38:39]
	v_lshl_add_u64 v[30:31], v[30:31], 0, v[32:33]
	global_load_dwordx4 v[30:33], v[30:31], off
	s_mov_b32 s1, s13
	v_or_b32_e32 v36, s5, v68
	v_lshl_add_u64 v[34:35], s[0:1], 1, v[42:43]
	v_lshlrev_b32_e32 v38, 13, v36
	v_lshl_add_u64 v[36:37], v[34:35], 0, v[38:39]
	s_mov_b64 s[0:1], 0
	s_waitcnt vmcnt(7)
	ds_write2_b32 v72, v2, v3 offset1:1
	ds_write2_b32 v72, v4, v5 offset0:2 offset1:3
	s_waitcnt vmcnt(6)
	ds_write2_b32 v73, v6, v7 offset1:1
	ds_write2_b32 v74, v8, v9 offset1:1
	s_waitcnt vmcnt(5)
	ds_write2_b32 v75, v10, v11 offset1:1
	ds_write2_b32 v76, v12, v13 offset1:1
	s_waitcnt vmcnt(4)
	ds_write2_b32 v77, v14, v15 offset1:1
	ds_write2_b32 v78, v16, v17 offset1:1
	s_waitcnt vmcnt(3)
	ds_write2_b32 v79, v18, v19 offset1:1
	ds_write2_b32 v80, v20, v21 offset1:1
	s_waitcnt vmcnt(2)
	ds_write2_b32 v81, v22, v23 offset1:1
	ds_write2_b32 v82, v24, v25 offset1:1
	s_waitcnt vmcnt(1)
	ds_write2_b32 v83, v26, v27 offset1:1
	ds_write2_b32 v84, v28, v29 offset1:1
	s_waitcnt vmcnt(0)
	ds_write2_b32 v85, v30, v31 offset1:1
	ds_write2_b32 v86, v32, v33 offset1:1
	s_waitcnt lgkmcnt(0)
	ds_read2_b32 v[6:7], v1 offset0:33 offset1:41
	ds_read2_b32 v[8:9], v1 offset1:8
	ds_read2_b32 v[10:11], v1 offset0:66 offset1:74
	ds_read2_b32 v[12:13], v1 offset0:99 offset1:107
	ds_read2_b32 v[14:15], v1 offset0:132 offset1:140
	ds_read2_b32 v[16:17], v1 offset0:165 offset1:173
	ds_read2_b32 v[18:19], v1 offset0:198 offset1:206
	ds_read2_b32 v[20:21], v1 offset0:231 offset1:239
	s_waitcnt lgkmcnt(6)
	v_bfe_u32 v2, v8, 16, 1
	v_bfe_u32 v3, v6, 16, 1
	s_waitcnt lgkmcnt(5)
	v_bfe_u32 v4, v10, 16, 1
	s_waitcnt lgkmcnt(3)
	v_bfe_u32 v22, v14, 16, 1
	s_waitcnt lgkmcnt(1)
	v_bfe_u32 v24, v18, 16, 1
	v_bfe_u32 v5, v12, 16, 1
	v_bfe_u32 v23, v16, 16, 1
	s_waitcnt lgkmcnt(0)
	v_bfe_u32 v25, v20, 16, 1
	v_add3_u32 v2, v8, v2, s8
	v_add3_u32 v3, v6, v3, s8
	v_add3_u32 v4, v10, v4, s8
	v_add3_u32 v6, v14, v22, s8
	v_add3_u32 v10, v18, v24, s8
	v_add3_u32 v5, v12, v5, s8
	v_add3_u32 v8, v16, v23, s8
	v_add3_u32 v12, v20, v25, s8
	v_lshrrev_b32_e32 v2, 16, v2
	v_lshrrev_b32_e32 v4, 16, v4
	v_lshrrev_b32_e32 v6, 16, v6
	v_lshrrev_b32_e32 v10, 16, v10
	v_and_or_b32 v2, v3, s9, v2
	v_and_or_b32 v3, v5, s9, v4
	v_and_or_b32 v4, v8, s9, v6
	v_and_or_b32 v5, v12, s9, v10
	global_store_dwordx4 v[36:37], v[2:5], off nt
	v_bfe_u32 v6, v21, 16, 1
	v_or_b32_e32 v8, s5, v69
	v_bfe_u32 v2, v9, 16, 1
	v_add3_u32 v2, v9, v2, s8
	v_bfe_u32 v3, v7, 16, 1
	v_lshrrev_b32_e32 v2, 16, v2
	v_add3_u32 v3, v7, v3, s8
	v_and_or_b32 v2, v3, s9, v2
	v_bfe_u32 v3, v11, 16, 1
	v_add3_u32 v3, v11, v3, s8
	v_bfe_u32 v4, v13, 16, 1
	v_lshrrev_b32_e32 v3, 16, v3
	v_add3_u32 v4, v13, v4, s8
	v_and_or_b32 v3, v4, s9, v3
	v_bfe_u32 v4, v15, 16, 1
	v_add3_u32 v4, v15, v4, s8
	v_bfe_u32 v5, v17, 16, 1
	v_lshrrev_b32_e32 v4, 16, v4
	v_add3_u32 v5, v17, v5, s8
	v_and_or_b32 v4, v5, s9, v4
	v_bfe_u32 v5, v19, 16, 1
	v_add3_u32 v5, v19, v5, s8
	v_lshrrev_b32_e32 v5, 16, v5
	v_add3_u32 v6, v21, v6, s8
	v_lshlrev_b32_e32 v38, 13, v8
	v_and_or_b32 v5, v6, s9, v5
	ds_read2_b32 v[6:7], v1 offset0:16 offset1:24
	v_lshl_add_u64 v[8:9], v[34:35], 0, v[38:39]
	global_store_dwordx4 v[8:9], v[2:5], off nt
	ds_read2_b32 v[8:9], v1 offset0:49 offset1:57
	ds_read2_b32 v[10:11], v1 offset0:82 offset1:90
	ds_read2_b32 v[12:13], v1 offset0:115 offset1:123
	s_waitcnt lgkmcnt(3)
	v_bfe_u32 v2, v6, 16, 1
	v_add3_u32 v2, v6, v2, s8
	s_waitcnt lgkmcnt(2)
	v_bfe_u32 v3, v8, 16, 1
	ds_read2_b32 v[14:15], v1 offset0:148 offset1:156
	v_lshrrev_b32_e32 v2, 16, v2
	v_add3_u32 v3, v8, v3, s8
	ds_read2_b32 v[16:17], v1 offset0:181 offset1:189
	v_and_or_b32 v2, v3, s9, v2
	s_waitcnt lgkmcnt(3)
	v_bfe_u32 v3, v10, 16, 1
	v_add3_u32 v3, v10, v3, s8
	s_waitcnt lgkmcnt(2)
	v_bfe_u32 v4, v12, 16, 1
	ds_read2_b32 v[18:19], v1 offset0:214 offset1:222
	v_lshrrev_b32_e32 v3, 16, v3
	v_add3_u32 v4, v12, v4, s8
	ds_read2_b32 v[20:21], v1 offset0:247 offset1:255
	v_and_or_b32 v3, v4, s9, v3
	s_waitcnt lgkmcnt(3)
	v_bfe_u32 v4, v14, 16, 1
	v_add3_u32 v4, v14, v4, s8
	s_waitcnt lgkmcnt(2)
	v_bfe_u32 v5, v16, 16, 1
	v_lshrrev_b32_e32 v4, 16, v4
	v_add3_u32 v5, v16, v5, s8
	v_and_or_b32 v4, v5, s9, v4
	s_waitcnt lgkmcnt(1)
	v_bfe_u32 v5, v18, 16, 1
	v_add3_u32 v5, v18, v5, s8
	s_waitcnt lgkmcnt(0)
	v_bfe_u32 v6, v20, 16, 1
	v_lshrrev_b32_e32 v5, 16, v5
	v_add3_u32 v6, v20, v6, s8
	v_and_or_b32 v5, v6, s9, v5
	v_or_b32_e32 v6, s5, v70
	v_lshlrev_b32_e32 v38, 13, v6
	v_lshl_add_u64 v[22:23], v[34:35], 0, v[38:39]
	global_store_dwordx4 v[22:23], v[2:5], off nt
	v_bfe_u32 v6, v21, 16, 1
	v_add3_u32 v6, v21, v6, s8
	v_bfe_u32 v2, v7, 16, 1
	v_add3_u32 v2, v7, v2, s8
	v_bfe_u32 v3, v9, 16, 1
	v_lshrrev_b32_e32 v2, 16, v2
	v_add3_u32 v3, v9, v3, s8
	v_and_or_b32 v2, v3, s9, v2
	v_bfe_u32 v3, v11, 16, 1
	v_add3_u32 v3, v11, v3, s8
	v_bfe_u32 v4, v13, 16, 1
	v_lshrrev_b32_e32 v3, 16, v3
	v_add3_u32 v4, v13, v4, s8
	v_and_or_b32 v3, v4, s9, v3
	v_bfe_u32 v4, v15, 16, 1
	v_add3_u32 v4, v15, v4, s8
	v_bfe_u32 v5, v17, 16, 1
	v_lshrrev_b32_e32 v4, 16, v4
	v_add3_u32 v5, v17, v5, s8
	v_and_or_b32 v4, v5, s9, v4
	v_bfe_u32 v5, v19, 16, 1
	v_add3_u32 v5, v19, v5, s8
	v_lshrrev_b32_e32 v5, 16, v5
	v_and_or_b32 v5, v6, s9, v5
	v_or_b32_e32 v6, s5, v71
	v_lshlrev_b32_e32 v38, 13, v6
	v_lshl_add_u64 v[6:7], v[34:35], 0, v[38:39]
	global_store_dwordx4 v[6:7], v[2:5], off nt
	s_waitcnt lgkmcnt(0)

.LBB0_568:
	s_waitcnt vmcnt(1)
	v_add_u32_e32 v2, 0x840, v87
	ds_write2_b32 v2, v16, v17 offset1:1
	v_add_u32_e32 v2, 0x848, v87
	ds_write2_b32 v2, v14, v15 offset1:1
	v_add_u32_e32 v2, 0xc60, v87
	ds_write2_b32 v2, v10, v11 offset1:1
	v_add_u32_e32 v2, 0xc68, v87
	ds_write2_b32 v2, v12, v13 offset1:1
	s_waitcnt lgkmcnt(0)
	s_waitcnt vmcnt(0)
	ds_read2_b32 v[6:7], v1 offset1:8
	ds_read2_b32 v[10:11], v1 offset0:33 offset1:41
	ds_read2_b32 v[12:13], v1 offset0:66 offset1:74
	ds_read2_b32 v[14:15], v1 offset0:99 offset1:107
	ds_read2_b32 v[16:17], v1 offset0:132 offset1:140
	s_waitcnt lgkmcnt(4)
	v_bfe_u32 v2, v6, 16, 1
	v_add3_u32 v2, v6, v2, s8
	s_waitcnt lgkmcnt(3)
	v_bfe_u32 v3, v10, 16, 1
	v_lshrrev_b32_e32 v2, 16, v2
	v_add3_u32 v3, v10, v3, s8
	ds_read2_b32 v[18:19], v1 offset0:165 offset1:173
	v_and_or_b32 v2, v3, s9, v2
	s_waitcnt lgkmcnt(3)
	v_bfe_u32 v3, v12, 16, 1
	v_add3_u32 v3, v12, v3, s8
	s_waitcnt lgkmcnt(2)
	v_bfe_u32 v4, v14, 16, 1
	ds_read2_b32 v[20:21], v1 offset0:198 offset1:206
	v_lshrrev_b32_e32 v3, 16, v3
	v_add3_u32 v4, v14, v4, s8
	ds_read2_b32 v[22:23], v1 offset0:231 offset1:239
	v_and_or_b32 v3, v4, s9, v3
	s_waitcnt lgkmcnt(3)
	v_bfe_u32 v4, v16, 16, 1
	v_add3_u32 v4, v16, v4, s8
	s_waitcnt lgkmcnt(2)
	v_bfe_u32 v5, v18, 16, 1
	v_lshrrev_b32_e32 v4, 16, v4
	v_add3_u32 v5, v18, v5, s8
	v_and_or_b32 v4, v5, s9, v4
	s_waitcnt lgkmcnt(1)
	v_bfe_u32 v5, v20, 16, 1
	v_add3_u32 v5, v20, v5, s8
	s_waitcnt lgkmcnt(0)
	v_bfe_u32 v6, v22, 16, 1
	v_lshrrev_b32_e32 v5, 16, v5
	v_add3_u32 v6, v22, v6, s8
	s_lshl_b32 s12, s28, 1
	v_and_or_b32 v5, v6, s9, v5
	v_or_b32_e32 v6, s7, v68
	v_lshl_add_u64 v[8:9], v[46:47], 0, s[12:13]
	v_lshlrev_b32_e32 v38, 11, v6
	v_lshl_add_u64 v[24:25], v[8:9], 0, v[38:39]
	global_store_dwordx4 v[24:25], v[2:5], off nt
	v_bfe_u32 v6, v23, 16, 1
	v_or_b32_e32 v10, s7, v69
	v_bfe_u32 v2, v7, 16, 1
	v_add3_u32 v2, v7, v2, s8
	v_bfe_u32 v3, v11, 16, 1
	v_lshrrev_b32_e32 v2, 16, v2
	v_add3_u32 v3, v11, v3, s8
	v_and_or_b32 v2, v3, s9, v2
	v_bfe_u32 v3, v13, 16, 1
	v_add3_u32 v3, v13, v3, s8
	v_bfe_u32 v4, v15, 16, 1
	v_lshrrev_b32_e32 v3, 16, v3
	v_add3_u32 v4, v15, v4, s8
	v_and_or_b32 v3, v4, s9, v3
	v_bfe_u32 v4, v17, 16, 1
	v_add3_u32 v4, v17, v4, s8
	v_bfe_u32 v5, v19, 16, 1
	v_lshrrev_b32_e32 v4, 16, v4
	v_add3_u32 v5, v19, v5, s8
	v_and_or_b32 v4, v5, s9, v4
	v_bfe_u32 v5, v21, 16, 1
	v_add3_u32 v5, v21, v5, s8
	v_lshrrev_b32_e32 v5, 16, v5
	v_add3_u32 v6, v23, v6, s8
	v_lshlrev_b32_e32 v38, 11, v10
	v_and_or_b32 v5, v6, s9, v5
	ds_read2_b32 v[6:7], v1 offset0:16 offset1:24
	v_lshl_add_u64 v[10:11], v[8:9], 0, v[38:39]
	global_store_dwordx4 v[10:11], v[2:5], off nt
	ds_read2_b32 v[10:11], v1 offset0:49 offset1:57
	ds_read2_b32 v[12:13], v1 offset0:82 offset1:90
	ds_read2_b32 v[14:15], v1 offset0:115 offset1:123
	s_waitcnt lgkmcnt(3)
	v_bfe_u32 v2, v6, 16, 1
	v_add3_u32 v2, v6, v2, s8
	s_waitcnt lgkmcnt(2)
	v_bfe_u32 v3, v10, 16, 1
	ds_read2_b32 v[16:17], v1 offset0:148 offset1:156
	v_lshrrev_b32_e32 v2, 16, v2
	v_add3_u32 v3, v10, v3, s8
	ds_read2_b32 v[18:19], v1 offset0:181 offset1:189
	v_and_or_b32 v2, v3, s9, v2
	s_waitcnt lgkmcnt(3)
	v_bfe_u32 v3, v12, 16, 1
	v_add3_u32 v3, v12, v3, s8
	s_waitcnt lgkmcnt(2)
	v_bfe_u32 v4, v14, 16, 1
	ds_read2_b32 v[20:21], v1 offset0:214 offset1:222
	v_lshrrev_b32_e32 v3, 16, v3
	v_add3_u32 v4, v14, v4, s8
	ds_read2_b32 v[22:23], v1 offset0:247 offset1:255
	v_and_or_b32 v3, v4, s9, v3
	s_waitcnt lgkmcnt(3)
	v_bfe_u32 v4, v16, 16, 1
	v_add3_u32 v4, v16, v4, s8
	s_waitcnt lgkmcnt(2)
	v_bfe_u32 v5, v18, 16, 1
	v_lshrrev_b32_e32 v4, 16, v4
	v_add3_u32 v5, v18, v5, s8
	v_and_or_b32 v4, v5, s9, v4
	s_waitcnt lgkmcnt(1)
	v_bfe_u32 v5, v20, 16, 1
	v_add3_u32 v5, v20, v5, s8
	s_waitcnt lgkmcnt(0)
	v_bfe_u32 v6, v22, 16, 1
	v_lshrrev_b32_e32 v5, 16, v5
	v_add3_u32 v6, v22, v6, s8
	v_and_or_b32 v5, v6, s9, v5
	v_or_b32_e32 v6, s7, v70
	v_lshlrev_b32_e32 v38, 11, v6
	v_lshl_add_u64 v[24:25], v[8:9], 0, v[38:39]
	global_store_dwordx4 v[24:25], v[2:5], off nt
	v_bfe_u32 v6, v23, 16, 1
	v_add3_u32 v6, v23, v6, s8
	v_bfe_u32 v2, v7, 16, 1
	v_add3_u32 v2, v7, v2, s8
	v_bfe_u32 v3, v11, 16, 1
	v_lshrrev_b32_e32 v2, 16, v2
	v_add3_u32 v3, v11, v3, s8
	v_and_or_b32 v2, v3, s9, v2
	v_bfe_u32 v3, v13, 16, 1
	v_add3_u32 v3, v13, v3, s8
	v_bfe_u32 v4, v15, 16, 1
	v_lshrrev_b32_e32 v3, 16, v3
	v_add3_u32 v4, v15, v4, s8
	v_and_or_b32 v3, v4, s9, v3
	v_bfe_u32 v4, v17, 16, 1
	v_add3_u32 v4, v17, v4, s8
	v_bfe_u32 v5, v19, 16, 1
	v_lshrrev_b32_e32 v4, 16, v4
	v_add3_u32 v5, v19, v5, s8
	v_and_or_b32 v4, v5, s9, v4
	v_bfe_u32 v5, v21, 16, 1
	v_add3_u32 v5, v21, v5, s8
	v_lshrrev_b32_e32 v5, 16, v5
	v_and_or_b32 v5, v6, s9, v5
	v_or_b32_e32 v6, s7, v71
	v_lshlrev_b32_e32 v38, 11, v6
	v_lshl_add_u64 v[6:7], v[8:9], 0, v[38:39]
	global_store_dwordx4 v[6:7], v[2:5], off nt
	s_waitcnt lgkmcnt(0)

.LBB0_570:
	s_andn2_b64 vcc, exec, s[0:1]
	s_cbranch_vccnz .LBB0_572
	s_lshl_b32 s0, s6, 1
	s_add_i32 s0, s0, 0x1e400
	s_and_b32 s1, s0, 0x1ffc0
	s_lshl_b32 s0, s6, 5
	s_and_b32 s0, s0, 0x3e0
	v_or_b32_e32 v4, s1, v68
	s_lshl_b32 s12, s0, 2
	v_lshl_add_u64 v[2:3], v[48:49], 0, s[12:13]
	v_lshlrev_b32_e32 v38, 12, v4
	v_lshl_add_u64 v[30:31], v[2:3], 0, v[38:39]
	v_add_co_u32_e32 v10, vcc, 0x8000, v30
	v_or_b32_e32 v36, s0, v68
	s_nop 0
	v_addc_co_u32_e32 v11, vcc, 0, v31, vcc
	v_add_co_u32_e32 v18, vcc, 0x10000, v30
	global_load_dwordx4 v[2:5], v[30:31], off
	global_load_dwordx4 v[6:9], v[10:11], off
	v_addc_co_u32_e32 v19, vcc, 0, v31, vcc
	v_add_co_u32_e32 v20, vcc, 0x18000, v30
	s_lshl_b32 s12, s1, 1
	s_nop 0
	v_addc_co_u32_e32 v21, vcc, 0, v31, vcc
	v_add_co_u32_e32 v26, vcc, s16, v30
	global_load_dwordx4 v[10:13], v[18:19], off
	global_load_dwordx4 v[14:17], v[20:21], off
	v_addc_co_u32_e32 v27, vcc, 0, v31, vcc
	v_add_co_u32_e32 v28, vcc, 0x28000, v30
	v_lshl_add_u64 v[34:35], v[50:51], 0, s[12:13]
	s_nop 0
	v_addc_co_u32_e32 v29, vcc, 0, v31, vcc
	global_load_dwordx4 v[18:21], v[26:27], off
	global_load_dwordx4 v[22:25], v[28:29], off
	v_add_co_u32_e32 v26, vcc, 0x30000, v30
	v_lshlrev_b32_e32 v38, 11, v36
	s_nop 0
	v_addc_co_u32_e32 v27, vcc, 0, v31, vcc
	global_load_dwordx4 v[26:29], v[26:27], off
	v_add_co_u32_e32 v30, vcc, 0x38000, v30
	s_nop 1
	v_addc_co_u32_e32 v31, vcc, 0, v31, vcc
	global_load_dwordx4 v[30:33], v[30:31], off
	s_waitcnt vmcnt(7)
	ds_write2_b32 v72, v2, v3 offset1:1
	ds_write2_b32 v72, v4, v5 offset0:2 offset1:3
	s_waitcnt vmcnt(6)
	ds_write2_b32 v73, v6, v7 offset1:1
	ds_write2_b32 v74, v8, v9 offset1:1
	s_waitcnt vmcnt(5)
	ds_write2_b32 v75, v10, v11 offset1:1
	ds_write2_b32 v76, v12, v13 offset1:1
	s_waitcnt vmcnt(4)
	ds_write2_b32 v77, v14, v15 offset1:1
	ds_write2_b32 v78, v16, v17 offset1:1
	s_waitcnt vmcnt(3)
	ds_write2_b32 v79, v18, v19 offset1:1
	ds_write2_b32 v80, v20, v21 offset1:1
	s_waitcnt vmcnt(2)
	ds_write2_b32 v81, v22, v23 offset1:1
	ds_write2_b32 v82, v24, v25 offset1:1
	s_waitcnt vmcnt(1)
	ds_write2_b32 v83, v26, v27 offset1:1
	ds_write2_b32 v84, v28, v29 offset1:1
	s_waitcnt vmcnt(0)
	ds_write2_b32 v85, v30, v31 offset1:1
	ds_write2_b32 v86, v32, v33 offset1:1
	s_waitcnt lgkmcnt(0)
	ds_read2_b32 v[6:7], v1 offset0:33 offset1:41
	ds_read2_b32 v[8:9], v1 offset1:8
	ds_read2_b32 v[10:11], v1 offset0:66 offset1:74
	ds_read2_b32 v[12:13], v1 offset0:99 offset1:107
	ds_read2_b32 v[14:15], v1 offset0:132 offset1:140
	ds_read2_b32 v[16:17], v1 offset0:165 offset1:173
	ds_read2_b32 v[18:19], v1 offset0:198 offset1:206
	ds_read2_b32 v[20:21], v1 offset0:231 offset1:239
	s_waitcnt lgkmcnt(6)
	v_bfe_u32 v2, v8, 16, 1
	v_bfe_u32 v3, v6, 16, 1
	s_waitcnt lgkmcnt(5)
	v_bfe_u32 v4, v10, 16, 1
	s_waitcnt lgkmcnt(3)
	v_bfe_u32 v22, v14, 16, 1
	s_waitcnt lgkmcnt(1)
	v_bfe_u32 v24, v18, 16, 1
	v_bfe_u32 v5, v12, 16, 1
	v_bfe_u32 v23, v16, 16, 1
	s_waitcnt lgkmcnt(0)
	v_bfe_u32 v25, v20, 16, 1
	v_add3_u32 v2, v8, v2, s8
	v_add3_u32 v3, v6, v3, s8
	v_add3_u32 v4, v10, v4, s8
	v_add3_u32 v6, v14, v22, s8
	v_add3_u32 v10, v18, v24, s8
	v_add3_u32 v5, v12, v5, s8
	v_add3_u32 v8, v16, v23, s8
	v_add3_u32 v12, v20, v25, s8
	v_lshrrev_b32_e32 v2, 16, v2
	v_lshrrev_b32_e32 v4, 16, v4
	v_lshrrev_b32_e32 v6, 16, v6
	v_lshrrev_b32_e32 v10, 16, v10
	v_and_or_b32 v2, v3, s9, v2
	v_and_or_b32 v3, v5, s9, v4
	v_and_or_b32 v4, v8, s9, v6
	v_and_or_b32 v5, v12, s9, v10
	v_lshl_add_u64 v[22:23], v[34:35], 0, v[38:39]
	global_store_dwordx4 v[22:23], v[2:5], off nt
	v_bfe_u32 v6, v21, 16, 1
	v_or_b32_e32 v8, s0, v69
	v_bfe_u32 v2, v9, 16, 1
	v_add3_u32 v2, v9, v2, s8
	v_bfe_u32 v3, v7, 16, 1
	v_lshrrev_b32_e32 v2, 16, v2
	v_add3_u32 v3, v7, v3, s8
	v_and_or_b32 v2, v3, s9, v2
	v_bfe_u32 v3, v11, 16, 1
	v_add3_u32 v3, v11, v3, s8
	v_bfe_u32 v4, v13, 16, 1
	v_lshrrev_b32_e32 v3, 16, v3
	v_add3_u32 v4, v13, v4, s8
	v_and_or_b32 v3, v4, s9, v3
	v_bfe_u32 v4, v15, 16, 1
	v_add3_u32 v4, v15, v4, s8
	v_bfe_u32 v5, v17, 16, 1
	v_lshrrev_b32_e32 v4, 16, v4
	v_add3_u32 v5, v17, v5, s8
	v_and_or_b32 v4, v5, s9, v4
	v_bfe_u32 v5, v19, 16, 1
	v_add3_u32 v5, v19, v5, s8
	v_lshrrev_b32_e32 v5, 16, v5
	v_add3_u32 v6, v21, v6, s8
	v_lshlrev_b32_e32 v38, 11, v8
	v_and_or_b32 v5, v6, s9, v5
	ds_read2_b32 v[6:7], v1 offset0:16 offset1:24
	v_lshl_add_u64 v[8:9], v[34:35], 0, v[38:39]
	global_store_dwordx4 v[8:9], v[2:5], off nt
	ds_read2_b32 v[8:9], v1 offset0:49 offset1:57
	ds_read2_b32 v[10:11], v1 offset0:82 offset1:90
	ds_read2_b32 v[12:13], v1 offset0:115 offset1:123
	s_waitcnt lgkmcnt(3)
	v_bfe_u32 v2, v6, 16, 1
	v_add3_u32 v2, v6, v2, s8
	s_waitcnt lgkmcnt(2)
	v_bfe_u32 v3, v8, 16, 1
	ds_read2_b32 v[14:15], v1 offset0:148 offset1:156
	v_lshrrev_b32_e32 v2, 16, v2
	v_add3_u32 v3, v8, v3, s8
	ds_read2_b32 v[16:17], v1 offset0:181 offset1:189
	v_and_or_b32 v2, v3, s9, v2
	s_waitcnt lgkmcnt(3)
	v_bfe_u32 v3, v10, 16, 1
	v_add3_u32 v3, v10, v3, s8
	s_waitcnt lgkmcnt(2)
	v_bfe_u32 v4, v12, 16, 1
	ds_read2_b32 v[18:19], v1 offset0:214 offset1:222
	v_lshrrev_b32_e32 v3, 16, v3
	v_add3_u32 v4, v12, v4, s8
	ds_read2_b32 v[20:21], v1 offset0:247 offset1:255
	v_and_or_b32 v3, v4, s9, v3
	s_waitcnt lgkmcnt(3)
	v_bfe_u32 v4, v14, 16, 1
	v_add3_u32 v4, v14, v4, s8
	s_waitcnt lgkmcnt(2)
	v_bfe_u32 v5, v16, 16, 1
	v_lshrrev_b32_e32 v4, 16, v4
	v_add3_u32 v5, v16, v5, s8
	v_and_or_b32 v4, v5, s9, v4
	s_waitcnt lgkmcnt(1)
	v_bfe_u32 v5, v18, 16, 1
	v_add3_u32 v5, v18, v5, s8
	s_waitcnt lgkmcnt(0)
	v_bfe_u32 v6, v20, 16, 1
	v_lshrrev_b32_e32 v5, 16, v5
	v_add3_u32 v6, v20, v6, s8
	v_and_or_b32 v5, v6, s9, v5
	v_or_b32_e32 v6, s0, v70
	v_lshlrev_b32_e32 v38, 11, v6
	v_lshl_add_u64 v[22:23], v[34:35], 0, v[38:39]
	global_store_dwordx4 v[22:23], v[2:5], off nt
	v_bfe_u32 v6, v21, 16, 1
	v_add3_u32 v6, v21, v6, s8
	v_bfe_u32 v2, v7, 16, 1
	v_add3_u32 v2, v7, v2, s8
	v_bfe_u32 v3, v9, 16, 1
	v_lshrrev_b32_e32 v2, 16, v2
	v_add3_u32 v3, v9, v3, s8
	v_and_or_b32 v2, v3, s9, v2
	v_bfe_u32 v3, v11, 16, 1
	v_add3_u32 v3, v11, v3, s8
	v_bfe_u32 v4, v13, 16, 1
	v_lshrrev_b32_e32 v3, 16, v3
	v_add3_u32 v4, v13, v4, s8
	v_and_or_b32 v3, v4, s9, v3
	v_bfe_u32 v4, v15, 16, 1
	v_add3_u32 v4, v15, v4, s8
	v_bfe_u32 v5, v17, 16, 1
	v_lshrrev_b32_e32 v4, 16, v4
	v_add3_u32 v5, v17, v5, s8
	v_and_or_b32 v4, v5, s9, v4
	v_bfe_u32 v5, v19, 16, 1
	v_add3_u32 v5, v19, v5, s8
	v_lshrrev_b32_e32 v5, 16, v5
	v_and_or_b32 v5, v6, s9, v5
	v_or_b32_e32 v6, s0, v71
	v_lshlrev_b32_e32 v38, 11, v6
	v_lshl_add_u64 v[6:7], v[34:35], 0, v[38:39]
	global_store_dwordx4 v[6:7], v[2:5], off nt
	s_waitcnt lgkmcnt(0)

.LBB0_573:
	s_andn2_b64 vcc, exec, s[0:1]
	s_cbranch_vccnz .LBB0_575
	s_lshl_b32 s0, s6, 1
	s_add_i32 s0, s0, 0x1ec00
	s_and_b32 s1, s0, 0x1ffc0
	s_lshl_b32 s0, s6, 5
	s_and_b32 s0, s0, 0x3e0
	v_or_b32_e32 v4, s1, v68
	s_lshl_b32 s12, s0, 2
	v_lshl_add_u64 v[2:3], v[52:53], 0, s[12:13]
	v_lshlrev_b32_e32 v38, 12, v4
	v_lshl_add_u64 v[30:31], v[2:3], 0, v[38:39]
	v_add_co_u32_e32 v10, vcc, 0x8000, v30
	v_or_b32_e32 v36, s0, v68
	s_nop 0
	v_addc_co_u32_e32 v11, vcc, 0, v31, vcc
	v_add_co_u32_e32 v18, vcc, 0x10000, v30
	global_load_dwordx4 v[2:5], v[30:31], off
	global_load_dwordx4 v[6:9], v[10:11], off
	v_addc_co_u32_e32 v19, vcc, 0, v31, vcc
	v_add_co_u32_e32 v20, vcc, 0x18000, v30
	s_lshl_b32 s12, s1, 1
	s_nop 0
	v_addc_co_u32_e32 v21, vcc, 0, v31, vcc
	v_add_co_u32_e32 v26, vcc, s16, v30
	global_load_dwordx4 v[10:13], v[18:19], off
	global_load_dwordx4 v[14:17], v[20:21], off
	v_addc_co_u32_e32 v27, vcc, 0, v31, vcc
	v_add_co_u32_e32 v28, vcc, 0x28000, v30
	v_lshl_add_u64 v[34:35], v[54:55], 0, s[12:13]
	s_nop 0
	v_addc_co_u32_e32 v29, vcc, 0, v31, vcc
	global_load_dwordx4 v[18:21], v[26:27], off
	global_load_dwordx4 v[22:25], v[28:29], off
	v_add_co_u32_e32 v26, vcc, 0x30000, v30
	v_lshlrev_b32_e32 v38, 12, v36
	s_nop 0
	v_addc_co_u32_e32 v27, vcc, 0, v31, vcc
	global_load_dwordx4 v[26:29], v[26:27], off
	v_add_co_u32_e32 v30, vcc, 0x38000, v30
	s_nop 1
	v_addc_co_u32_e32 v31, vcc, 0, v31, vcc
	global_load_dwordx4 v[30:33], v[30:31], off
	s_waitcnt vmcnt(7)
	ds_write2_b32 v72, v2, v3 offset1:1
	ds_write2_b32 v72, v4, v5 offset0:2 offset1:3
	s_waitcnt vmcnt(6)
	ds_write2_b32 v73, v6, v7 offset1:1
	ds_write2_b32 v74, v8, v9 offset1:1
	s_waitcnt vmcnt(5)
	ds_write2_b32 v75, v10, v11 offset1:1
	ds_write2_b32 v76, v12, v13 offset1:1
	s_waitcnt vmcnt(4)
	ds_write2_b32 v77, v14, v15 offset1:1
	ds_write2_b32 v78, v16, v17 offset1:1
	s_waitcnt vmcnt(3)
	ds_write2_b32 v79, v18, v19 offset1:1
	ds_write2_b32 v80, v20, v21 offset1:1
	s_waitcnt vmcnt(2)
	ds_write2_b32 v81, v22, v23 offset1:1
	ds_write2_b32 v82, v24, v25 offset1:1
	s_waitcnt vmcnt(1)
	ds_write2_b32 v83, v26, v27 offset1:1
	ds_write2_b32 v84, v28, v29 offset1:1
	s_waitcnt vmcnt(0)
	ds_write2_b32 v85, v30, v31 offset1:1
	ds_write2_b32 v86, v32, v33 offset1:1
	s_waitcnt lgkmcnt(0)
	ds_read2_b32 v[6:7], v1 offset0:33 offset1:41
	ds_read2_b32 v[8:9], v1 offset1:8
	ds_read2_b32 v[10:11], v1 offset0:66 offset1:74
	ds_read2_b32 v[12:13], v1 offset0:99 offset1:107
	ds_read2_b32 v[14:15], v1 offset0:132 offset1:140
	ds_read2_b32 v[16:17], v1 offset0:165 offset1:173
	ds_read2_b32 v[18:19], v1 offset0:198 offset1:206
	ds_read2_b32 v[20:21], v1 offset0:231 offset1:239
	s_waitcnt lgkmcnt(6)
	v_bfe_u32 v2, v8, 16, 1
	v_bfe_u32 v3, v6, 16, 1
	s_waitcnt lgkmcnt(5)
	v_bfe_u32 v4, v10, 16, 1
	s_waitcnt lgkmcnt(3)
	v_bfe_u32 v22, v14, 16, 1
	s_waitcnt lgkmcnt(1)
	v_bfe_u32 v24, v18, 16, 1
	v_bfe_u32 v5, v12, 16, 1
	v_bfe_u32 v23, v16, 16, 1
	s_waitcnt lgkmcnt(0)
	v_bfe_u32 v25, v20, 16, 1
	v_add3_u32 v2, v8, v2, s8
	v_add3_u32 v3, v6, v3, s8
	v_add3_u32 v4, v10, v4, s8
	v_add3_u32 v6, v14, v22, s8
	v_add3_u32 v10, v18, v24, s8
	v_add3_u32 v5, v12, v5, s8
	v_add3_u32 v8, v16, v23, s8
	v_add3_u32 v12, v20, v25, s8
	v_lshrrev_b32_e32 v2, 16, v2
	v_lshrrev_b32_e32 v4, 16, v4
	v_lshrrev_b32_e32 v6, 16, v6
	v_lshrrev_b32_e32 v10, 16, v10
	v_and_or_b32 v2, v3, s9, v2
	v_and_or_b32 v3, v5, s9, v4
	v_and_or_b32 v4, v8, s9, v6
	v_and_or_b32 v5, v12, s9, v10
	v_lshl_add_u64 v[22:23], v[34:35], 0, v[38:39]
	global_store_dwordx4 v[22:23], v[2:5], off nt
	v_bfe_u32 v6, v21, 16, 1
	v_or_b32_e32 v8, s0, v69
	v_bfe_u32 v2, v9, 16, 1
	v_add3_u32 v2, v9, v2, s8
	v_bfe_u32 v3, v7, 16, 1
	v_lshrrev_b32_e32 v2, 16, v2
	v_add3_u32 v3, v7, v3, s8
	v_and_or_b32 v2, v3, s9, v2
	v_bfe_u32 v3, v11, 16, 1
	v_add3_u32 v3, v11, v3, s8
	v_bfe_u32 v4, v13, 16, 1
	v_lshrrev_b32_e32 v3, 16, v3
	v_add3_u32 v4, v13, v4, s8
	v_and_or_b32 v3, v4, s9, v3
	v_bfe_u32 v4, v15, 16, 1
	v_add3_u32 v4, v15, v4, s8
	v_bfe_u32 v5, v17, 16, 1
	v_lshrrev_b32_e32 v4, 16, v4
	v_add3_u32 v5, v17, v5, s8
	v_and_or_b32 v4, v5, s9, v4
	v_bfe_u32 v5, v19, 16, 1
	v_add3_u32 v5, v19, v5, s8
	v_lshrrev_b32_e32 v5, 16, v5
	v_add3_u32 v6, v21, v6, s8
	v_lshlrev_b32_e32 v38, 12, v8
	v_and_or_b32 v5, v6, s9, v5
	ds_read2_b32 v[6:7], v1 offset0:16 offset1:24
	v_lshl_add_u64 v[8:9], v[34:35], 0, v[38:39]
	global_store_dwordx4 v[8:9], v[2:5], off nt
	ds_read2_b32 v[8:9], v1 offset0:49 offset1:57
	ds_read2_b32 v[10:11], v1 offset0:82 offset1:90
	ds_read2_b32 v[12:13], v1 offset0:115 offset1:123
	s_waitcnt lgkmcnt(3)
	v_bfe_u32 v2, v6, 16, 1
	v_add3_u32 v2, v6, v2, s8
	s_waitcnt lgkmcnt(2)
	v_bfe_u32 v3, v8, 16, 1
	ds_read2_b32 v[14:15], v1 offset0:148 offset1:156
	v_lshrrev_b32_e32 v2, 16, v2
	v_add3_u32 v3, v8, v3, s8
	ds_read2_b32 v[16:17], v1 offset0:181 offset1:189
	v_and_or_b32 v2, v3, s9, v2
	s_waitcnt lgkmcnt(3)
	v_bfe_u32 v3, v10, 16, 1
	v_add3_u32 v3, v10, v3, s8
	s_waitcnt lgkmcnt(2)
	v_bfe_u32 v4, v12, 16, 1
	ds_read2_b32 v[18:19], v1 offset0:214 offset1:222
	v_lshrrev_b32_e32 v3, 16, v3
	v_add3_u32 v4, v12, v4, s8
	ds_read2_b32 v[20:21], v1 offset0:247 offset1:255
	v_and_or_b32 v3, v4, s9, v3
	s_waitcnt lgkmcnt(3)
	v_bfe_u32 v4, v14, 16, 1
	v_add3_u32 v4, v14, v4, s8
	s_waitcnt lgkmcnt(2)
	v_bfe_u32 v5, v16, 16, 1
	v_lshrrev_b32_e32 v4, 16, v4
	v_add3_u32 v5, v16, v5, s8
	v_and_or_b32 v4, v5, s9, v4
	s_waitcnt lgkmcnt(1)
	v_bfe_u32 v5, v18, 16, 1
	v_add3_u32 v5, v18, v5, s8
	s_waitcnt lgkmcnt(0)
	v_bfe_u32 v6, v20, 16, 1
	v_lshrrev_b32_e32 v5, 16, v5
	v_add3_u32 v6, v20, v6, s8
	v_and_or_b32 v5, v6, s9, v5
	v_or_b32_e32 v6, s0, v70
	v_lshlrev_b32_e32 v38, 12, v6
	v_lshl_add_u64 v[22:23], v[34:35], 0, v[38:39]
	global_store_dwordx4 v[22:23], v[2:5], off nt
	v_bfe_u32 v6, v21, 16, 1
	v_add3_u32 v6, v21, v6, s8
	v_bfe_u32 v2, v7, 16, 1
	v_add3_u32 v2, v7, v2, s8
	v_bfe_u32 v3, v9, 16, 1
	v_lshrrev_b32_e32 v2, 16, v2
	v_add3_u32 v3, v9, v3, s8
	v_and_or_b32 v2, v3, s9, v2
	v_bfe_u32 v3, v11, 16, 1
	v_add3_u32 v3, v11, v3, s8
	v_bfe_u32 v4, v13, 16, 1
	v_lshrrev_b32_e32 v3, 16, v3
	v_add3_u32 v4, v13, v4, s8
	v_and_or_b32 v3, v4, s9, v3
	v_bfe_u32 v4, v15, 16, 1
	v_add3_u32 v4, v15, v4, s8
	v_bfe_u32 v5, v17, 16, 1
	v_lshrrev_b32_e32 v4, 16, v4
	v_add3_u32 v5, v17, v5, s8
	v_and_or_b32 v4, v5, s9, v4
	v_bfe_u32 v5, v19, 16, 1
	v_add3_u32 v5, v19, v5, s8
	v_lshrrev_b32_e32 v5, 16, v5
	v_and_or_b32 v5, v6, s9, v5
	v_or_b32_e32 v6, s0, v71
	v_lshlrev_b32_e32 v38, 12, v6
	v_lshl_add_u64 v[6:7], v[34:35], 0, v[38:39]
	global_store_dwordx4 v[6:7], v[2:5], off nt
	s_waitcnt lgkmcnt(0)

.LBB0_576:
	s_andn2_b64 vcc, exec, s[0:1]
	s_cbranch_vccnz .LBB0_578
	s_lshl_b32 s0, s6, 1
	s_add_i32 s0, s0, 0x1f000
	s_and_b32 s1, s0, 0x1ffc0
	s_lshl_b32 s0, s6, 5
	s_and_b32 s0, s0, 0x3e0
	v_or_b32_e32 v4, s1, v68
	s_lshl_b32 s12, s0, 2
	v_lshl_add_u64 v[2:3], v[56:57], 0, s[12:13]
	v_lshlrev_b32_e32 v38, 12, v4
	v_lshl_add_u64 v[30:31], v[2:3], 0, v[38:39]
	v_add_co_u32_e32 v10, vcc, 0x8000, v30
	v_or_b32_e32 v36, s0, v68
	s_nop 0
	v_addc_co_u32_e32 v11, vcc, 0, v31, vcc
	v_add_co_u32_e32 v18, vcc, 0x10000, v30
	global_load_dwordx4 v[2:5], v[30:31], off
	global_load_dwordx4 v[6:9], v[10:11], off
	v_addc_co_u32_e32 v19, vcc, 0, v31, vcc
	v_add_co_u32_e32 v20, vcc, 0x18000, v30
	s_lshl_b32 s12, s1, 1
	s_nop 0
	v_addc_co_u32_e32 v21, vcc, 0, v31, vcc
	v_add_co_u32_e32 v26, vcc, s16, v30
	global_load_dwordx4 v[10:13], v[18:19], off
	global_load_dwordx4 v[14:17], v[20:21], off
	v_addc_co_u32_e32 v27, vcc, 0, v31, vcc
	v_add_co_u32_e32 v28, vcc, 0x28000, v30
	v_lshl_add_u64 v[34:35], v[58:59], 0, s[12:13]
	s_nop 0
	v_addc_co_u32_e32 v29, vcc, 0, v31, vcc
	global_load_dwordx4 v[18:21], v[26:27], off
	global_load_dwordx4 v[22:25], v[28:29], off
	v_add_co_u32_e32 v26, vcc, 0x30000, v30
	v_lshlrev_b32_e32 v38, 11, v36
	s_nop 0
	v_addc_co_u32_e32 v27, vcc, 0, v31, vcc
	global_load_dwordx4 v[26:29], v[26:27], off
	v_add_co_u32_e32 v30, vcc, 0x38000, v30
	s_nop 1
	v_addc_co_u32_e32 v31, vcc, 0, v31, vcc
	global_load_dwordx4 v[30:33], v[30:31], off
	s_waitcnt vmcnt(7)
	ds_write2_b32 v72, v2, v3 offset1:1
	ds_write2_b32 v72, v4, v5 offset0:2 offset1:3
	s_waitcnt vmcnt(6)
	ds_write2_b32 v73, v6, v7 offset1:1
	ds_write2_b32 v74, v8, v9 offset1:1
	s_waitcnt vmcnt(5)
	ds_write2_b32 v75, v10, v11 offset1:1
	ds_write2_b32 v76, v12, v13 offset1:1
	s_waitcnt vmcnt(4)
	ds_write2_b32 v77, v14, v15 offset1:1
	ds_write2_b32 v78, v16, v17 offset1:1
	s_waitcnt vmcnt(3)
	ds_write2_b32 v79, v18, v19 offset1:1
	ds_write2_b32 v80, v20, v21 offset1:1
	s_waitcnt vmcnt(2)
	ds_write2_b32 v81, v22, v23 offset1:1
	ds_write2_b32 v82, v24, v25 offset1:1
	s_waitcnt vmcnt(1)
	ds_write2_b32 v83, v26, v27 offset1:1
	ds_write2_b32 v84, v28, v29 offset1:1
	s_waitcnt vmcnt(0)
	ds_write2_b32 v85, v30, v31 offset1:1
	ds_write2_b32 v86, v32, v33 offset1:1
	s_waitcnt lgkmcnt(0)
	ds_read2_b32 v[6:7], v1 offset0:33 offset1:41
	ds_read2_b32 v[8:9], v1 offset1:8
	ds_read2_b32 v[10:11], v1 offset0:66 offset1:74
	ds_read2_b32 v[12:13], v1 offset0:99 offset1:107
	ds_read2_b32 v[14:15], v1 offset0:132 offset1:140
	ds_read2_b32 v[16:17], v1 offset0:165 offset1:173
	ds_read2_b32 v[18:19], v1 offset0:198 offset1:206
	ds_read2_b32 v[20:21], v1 offset0:231 offset1:239
	s_waitcnt lgkmcnt(6)
	v_bfe_u32 v2, v8, 16, 1
	v_bfe_u32 v3, v6, 16, 1
	s_waitcnt lgkmcnt(5)
	v_bfe_u32 v4, v10, 16, 1
	s_waitcnt lgkmcnt(3)
	v_bfe_u32 v22, v14, 16, 1
	s_waitcnt lgkmcnt(1)
	v_bfe_u32 v24, v18, 16, 1
	v_bfe_u32 v5, v12, 16, 1
	v_bfe_u32 v23, v16, 16, 1
	s_waitcnt lgkmcnt(0)
	v_bfe_u32 v25, v20, 16, 1
	v_add3_u32 v2, v8, v2, s8
	v_add3_u32 v3, v6, v3, s8
	v_add3_u32 v4, v10, v4, s8
	v_add3_u32 v6, v14, v22, s8
	v_add3_u32 v10, v18, v24, s8
	v_add3_u32 v5, v12, v5, s8
	v_add3_u32 v8, v16, v23, s8
	v_add3_u32 v12, v20, v25, s8
	v_lshrrev_b32_e32 v2, 16, v2
	v_lshrrev_b32_e32 v4, 16, v4
	v_lshrrev_b32_e32 v6, 16, v6
	v_lshrrev_b32_e32 v10, 16, v10
	v_and_or_b32 v2, v3, s9, v2
	v_and_or_b32 v3, v5, s9, v4
	v_and_or_b32 v4, v8, s9, v6
	v_and_or_b32 v5, v12, s9, v10
	v_lshl_add_u64 v[22:23], v[34:35], 0, v[38:39]
	global_store_dwordx4 v[22:23], v[2:5], off nt
	v_bfe_u32 v6, v21, 16, 1
	v_or_b32_e32 v8, s0, v69
	v_bfe_u32 v2, v9, 16, 1
	v_add3_u32 v2, v9, v2, s8
	v_bfe_u32 v3, v7, 16, 1
	v_lshrrev_b32_e32 v2, 16, v2
	v_add3_u32 v3, v7, v3, s8
	v_and_or_b32 v2, v3, s9, v2
	v_bfe_u32 v3, v11, 16, 1
	v_add3_u32 v3, v11, v3, s8
	v_bfe_u32 v4, v13, 16, 1
	v_lshrrev_b32_e32 v3, 16, v3
	v_add3_u32 v4, v13, v4, s8
	v_and_or_b32 v3, v4, s9, v3
	v_bfe_u32 v4, v15, 16, 1
	v_add3_u32 v4, v15, v4, s8
	v_bfe_u32 v5, v17, 16, 1
	v_lshrrev_b32_e32 v4, 16, v4
	v_add3_u32 v5, v17, v5, s8
	v_and_or_b32 v4, v5, s9, v4
	v_bfe_u32 v5, v19, 16, 1
	v_add3_u32 v5, v19, v5, s8
	v_lshrrev_b32_e32 v5, 16, v5
	v_add3_u32 v6, v21, v6, s8
	v_lshlrev_b32_e32 v38, 11, v8
	v_and_or_b32 v5, v6, s9, v5
	ds_read2_b32 v[6:7], v1 offset0:16 offset1:24
	v_lshl_add_u64 v[8:9], v[34:35], 0, v[38:39]
	global_store_dwordx4 v[8:9], v[2:5], off nt
	ds_read2_b32 v[8:9], v1 offset0:49 offset1:57
	ds_read2_b32 v[10:11], v1 offset0:82 offset1:90
	ds_read2_b32 v[12:13], v1 offset0:115 offset1:123
	s_waitcnt lgkmcnt(3)
	v_bfe_u32 v2, v6, 16, 1
	v_add3_u32 v2, v6, v2, s8
	s_waitcnt lgkmcnt(2)
	v_bfe_u32 v3, v8, 16, 1
	ds_read2_b32 v[14:15], v1 offset0:148 offset1:156
	v_lshrrev_b32_e32 v2, 16, v2
	v_add3_u32 v3, v8, v3, s8
	ds_read2_b32 v[16:17], v1 offset0:181 offset1:189
	v_and_or_b32 v2, v3, s9, v2
	s_waitcnt lgkmcnt(3)
	v_bfe_u32 v3, v10, 16, 1
	v_add3_u32 v3, v10, v3, s8
	s_waitcnt lgkmcnt(2)
	v_bfe_u32 v4, v12, 16, 1
	ds_read2_b32 v[18:19], v1 offset0:214 offset1:222
	v_lshrrev_b32_e32 v3, 16, v3
	v_add3_u32 v4, v12, v4, s8
	ds_read2_b32 v[20:21], v1 offset0:247 offset1:255
	v_and_or_b32 v3, v4, s9, v3
	s_waitcnt lgkmcnt(3)
	v_bfe_u32 v4, v14, 16, 1
	v_add3_u32 v4, v14, v4, s8
	s_waitcnt lgkmcnt(2)
	v_bfe_u32 v5, v16, 16, 1
	v_lshrrev_b32_e32 v4, 16, v4
	v_add3_u32 v5, v16, v5, s8
	v_and_or_b32 v4, v5, s9, v4
	s_waitcnt lgkmcnt(1)
	v_bfe_u32 v5, v18, 16, 1
	v_add3_u32 v5, v18, v5, s8
	s_waitcnt lgkmcnt(0)
	v_bfe_u32 v6, v20, 16, 1
	v_lshrrev_b32_e32 v5, 16, v5
	v_add3_u32 v6, v20, v6, s8
	v_and_or_b32 v5, v6, s9, v5
	v_or_b32_e32 v6, s0, v70
	v_lshlrev_b32_e32 v38, 11, v6
	v_lshl_add_u64 v[22:23], v[34:35], 0, v[38:39]
	global_store_dwordx4 v[22:23], v[2:5], off nt
	v_bfe_u32 v6, v21, 16, 1
	v_add3_u32 v6, v21, v6, s8
	v_bfe_u32 v2, v7, 16, 1
	v_add3_u32 v2, v7, v2, s8
	v_bfe_u32 v3, v9, 16, 1
	v_lshrrev_b32_e32 v2, 16, v2
	v_add3_u32 v3, v9, v3, s8
	v_and_or_b32 v2, v3, s9, v2
	v_bfe_u32 v3, v11, 16, 1
	v_add3_u32 v3, v11, v3, s8
	v_bfe_u32 v4, v13, 16, 1
	v_lshrrev_b32_e32 v3, 16, v3
	v_add3_u32 v4, v13, v4, s8
	v_and_or_b32 v3, v4, s9, v3
	v_bfe_u32 v4, v15, 16, 1
	v_add3_u32 v4, v15, v4, s8
	v_bfe_u32 v5, v17, 16, 1
	v_lshrrev_b32_e32 v4, 16, v4
	v_add3_u32 v5, v17, v5, s8
	v_and_or_b32 v4, v5, s9, v4
	v_bfe_u32 v5, v19, 16, 1
	v_add3_u32 v5, v19, v5, s8
	v_lshrrev_b32_e32 v5, 16, v5
	v_and_or_b32 v5, v6, s9, v5
	v_or_b32_e32 v6, s0, v71
	v_lshlrev_b32_e32 v38, 11, v6
	v_lshl_add_u64 v[6:7], v[34:35], 0, v[38:39]
	global_store_dwordx4 v[6:7], v[2:5], off nt
	s_waitcnt lgkmcnt(0)

.LBB0_579:
	s_lshr_b32 s0, s6, 7
	s_mulk_i32 s0, 0x160
	s_and_b32 s1, s6, 0x7f
	s_add_i32 s0, s1, s0
	s_addk_i32 s0, 0xe0
	s_and_b32 s1, s0, 0xffff
	s_mul_i32 s1, s1, 0xba2f
	s_lshr_b32 s1, s1, 24
	s_mul_i32 s4, s1, 0x160
	s_sub_i32 s0, s0, s4
	s_lshl_b32 s0, s0, 5
	s_and_b32 s0, s0, 0xffe0
	v_lshl_or_b32 v4, s1, 6, v68
	s_lshl_b32 s12, s0, 2
	v_mul_u32_u24_e32 v4, 0x2c00, v4
	v_lshl_add_u64 v[2:3], v[60:61], 0, s[12:13]
	v_lshlrev_b32_e32 v38, 2, v4
	v_lshl_add_u64 v[30:31], v[2:3], 0, v[38:39]
	v_add_co_u32_e32 v10, vcc, s17, v30
	v_or_b32_e32 v36, s0, v68
	s_nop 0
	v_addc_co_u32_e32 v11, vcc, 0, v31, vcc
	v_add_co_u32_e32 v18, vcc, s18, v30
	global_load_dwordx4 v[2:5], v[30:31], off
	global_load_dwordx4 v[6:9], v[10:11], off
	v_addc_co_u32_e32 v19, vcc, 0, v31, vcc
	v_add_co_u32_e32 v20, vcc, s19, v30
	s_lshl_b32 s12, s1, 7
	s_nop 0
	v_addc_co_u32_e32 v21, vcc, 0, v31, vcc
	v_add_co_u32_e32 v26, vcc, s23, v30
	global_load_dwordx4 v[10:13], v[18:19], off
	global_load_dwordx4 v[14:17], v[20:21], off
	v_addc_co_u32_e32 v27, vcc, 0, v31, vcc
	v_add_co_u32_e32 v28, vcc, s24, v30
	v_lshl_add_u64 v[34:35], v[62:63], 0, s[12:13]
	s_nop 0
	v_addc_co_u32_e32 v29, vcc, 0, v31, vcc
	global_load_dwordx4 v[18:21], v[26:27], off
	global_load_dwordx4 v[22:25], v[28:29], off
	v_add_co_u32_e32 v26, vcc, s25, v30
	v_lshlrev_b32_e32 v38, 11, v36
	s_nop 0
	v_addc_co_u32_e32 v27, vcc, 0, v31, vcc
	global_load_dwordx4 v[26:29], v[26:27], off
	v_add_co_u32_e32 v30, vcc, s26, v30
	s_nop 1
	v_addc_co_u32_e32 v31, vcc, 0, v31, vcc
	global_load_dwordx4 v[30:33], v[30:31], off
	s_waitcnt vmcnt(7)
	ds_write2_b32 v72, v2, v3 offset1:1
	ds_write2_b32 v72, v4, v5 offset0:2 offset1:3
	s_waitcnt vmcnt(6)
	ds_write2_b32 v73, v6, v7 offset1:1
	ds_write2_b32 v74, v8, v9 offset1:1
	s_waitcnt vmcnt(5)
	ds_write2_b32 v75, v10, v11 offset1:1
	ds_write2_b32 v76, v12, v13 offset1:1
	s_waitcnt vmcnt(4)
	ds_write2_b32 v77, v14, v15 offset1:1
	ds_write2_b32 v78, v16, v17 offset1:1
	s_waitcnt vmcnt(3)
	ds_write2_b32 v79, v18, v19 offset1:1
	ds_write2_b32 v80, v20, v21 offset1:1
	s_waitcnt vmcnt(2)
	ds_write2_b32 v81, v22, v23 offset1:1
	ds_write2_b32 v82, v24, v25 offset1:1
	s_waitcnt vmcnt(1)
	ds_write2_b32 v83, v26, v27 offset1:1
	ds_write2_b32 v84, v28, v29 offset1:1
	s_waitcnt vmcnt(0)
	ds_write2_b32 v85, v30, v31 offset1:1
	ds_write2_b32 v86, v32, v33 offset1:1
	s_waitcnt lgkmcnt(0)
	ds_read2_b32 v[6:7], v1 offset0:33 offset1:41
	ds_read2_b32 v[8:9], v1 offset1:8
	ds_read2_b32 v[10:11], v1 offset0:66 offset1:74
	ds_read2_b32 v[12:13], v1 offset0:99 offset1:107
	ds_read2_b32 v[14:15], v1 offset0:132 offset1:140
	ds_read2_b32 v[16:17], v1 offset0:165 offset1:173
	ds_read2_b32 v[18:19], v1 offset0:198 offset1:206
	ds_read2_b32 v[20:21], v1 offset0:231 offset1:239
	s_waitcnt lgkmcnt(6)
	v_bfe_u32 v2, v8, 16, 1
	v_bfe_u32 v3, v6, 16, 1
	s_waitcnt lgkmcnt(5)
	v_bfe_u32 v4, v10, 16, 1
	s_waitcnt lgkmcnt(3)
	v_bfe_u32 v22, v14, 16, 1
	s_waitcnt lgkmcnt(1)
	v_bfe_u32 v24, v18, 16, 1
	v_bfe_u32 v5, v12, 16, 1
	v_bfe_u32 v23, v16, 16, 1
	s_waitcnt lgkmcnt(0)
	v_bfe_u32 v25, v20, 16, 1
	v_add3_u32 v2, v8, v2, s8
	v_add3_u32 v3, v6, v3, s8
	v_add3_u32 v4, v10, v4, s8
	v_add3_u32 v6, v14, v22, s8
	v_add3_u32 v10, v18, v24, s8
	v_add3_u32 v5, v12, v5, s8
	v_add3_u32 v8, v16, v23, s8
	v_add3_u32 v12, v20, v25, s8
	v_lshrrev_b32_e32 v2, 16, v2
	v_lshrrev_b32_e32 v4, 16, v4
	v_lshrrev_b32_e32 v6, 16, v6
	v_lshrrev_b32_e32 v10, 16, v10
	v_and_or_b32 v2, v3, s9, v2
	v_and_or_b32 v3, v5, s9, v4
	v_and_or_b32 v4, v8, s9, v6
	v_and_or_b32 v5, v12, s9, v10
	v_lshl_add_u64 v[22:23], v[34:35], 0, v[38:39]
	global_store_dwordx4 v[22:23], v[2:5], off nt
	v_bfe_u32 v6, v21, 16, 1
	v_or_b32_e32 v8, s0, v69
	v_bfe_u32 v2, v9, 16, 1
	v_add3_u32 v2, v9, v2, s8
	v_bfe_u32 v3, v7, 16, 1
	v_lshrrev_b32_e32 v2, 16, v2
	v_add3_u32 v3, v7, v3, s8
	v_and_or_b32 v2, v3, s9, v2
	v_bfe_u32 v3, v11, 16, 1
	v_add3_u32 v3, v11, v3, s8
	v_bfe_u32 v4, v13, 16, 1
	v_lshrrev_b32_e32 v3, 16, v3
	v_add3_u32 v4, v13, v4, s8
	v_and_or_b32 v3, v4, s9, v3
	v_bfe_u32 v4, v15, 16, 1
	v_add3_u32 v4, v15, v4, s8
	v_bfe_u32 v5, v17, 16, 1
	v_lshrrev_b32_e32 v4, 16, v4
	v_add3_u32 v5, v17, v5, s8
	v_and_or_b32 v4, v5, s9, v4
	v_bfe_u32 v5, v19, 16, 1
	v_add3_u32 v5, v19, v5, s8
	v_lshrrev_b32_e32 v5, 16, v5
	v_add3_u32 v6, v21, v6, s8
	v_lshlrev_b32_e32 v38, 11, v8
	v_and_or_b32 v5, v6, s9, v5
	ds_read2_b32 v[6:7], v1 offset0:16 offset1:24
	v_lshl_add_u64 v[8:9], v[34:35], 0, v[38:39]
	global_store_dwordx4 v[8:9], v[2:5], off nt
	ds_read2_b32 v[8:9], v1 offset0:49 offset1:57
	ds_read2_b32 v[10:11], v1 offset0:82 offset1:90
	ds_read2_b32 v[12:13], v1 offset0:115 offset1:123
	s_waitcnt lgkmcnt(3)
	v_bfe_u32 v2, v6, 16, 1
	v_add3_u32 v2, v6, v2, s8
	s_waitcnt lgkmcnt(2)
	v_bfe_u32 v3, v8, 16, 1
	ds_read2_b32 v[14:15], v1 offset0:148 offset1:156
	v_lshrrev_b32_e32 v2, 16, v2
	v_add3_u32 v3, v8, v3, s8
	ds_read2_b32 v[16:17], v1 offset0:181 offset1:189
	v_and_or_b32 v2, v3, s9, v2
	s_waitcnt lgkmcnt(3)
	v_bfe_u32 v3, v10, 16, 1
	v_add3_u32 v3, v10, v3, s8
	s_waitcnt lgkmcnt(2)
	v_bfe_u32 v4, v12, 16, 1
	ds_read2_b32 v[18:19], v1 offset0:214 offset1:222
	v_lshrrev_b32_e32 v3, 16, v3
	v_add3_u32 v4, v12, v4, s8
	ds_read2_b32 v[20:21], v1 offset0:247 offset1:255
	v_and_or_b32 v3, v4, s9, v3
	s_waitcnt lgkmcnt(3)
	v_bfe_u32 v4, v14, 16, 1
	v_add3_u32 v4, v14, v4, s8
	s_waitcnt lgkmcnt(2)
	v_bfe_u32 v5, v16, 16, 1
	v_lshrrev_b32_e32 v4, 16, v4
	v_add3_u32 v5, v16, v5, s8
	v_and_or_b32 v4, v5, s9, v4
	s_waitcnt lgkmcnt(1)
	v_bfe_u32 v5, v18, 16, 1
	v_add3_u32 v5, v18, v5, s8
	s_waitcnt lgkmcnt(0)
	v_bfe_u32 v6, v20, 16, 1
	v_lshrrev_b32_e32 v5, 16, v5
	v_add3_u32 v6, v20, v6, s8
	v_and_or_b32 v5, v6, s9, v5
	v_or_b32_e32 v6, s0, v70
	v_lshlrev_b32_e32 v38, 11, v6
	v_lshl_add_u64 v[22:23], v[34:35], 0, v[38:39]
	global_store_dwordx4 v[22:23], v[2:5], off nt
	v_bfe_u32 v6, v21, 16, 1
	v_add3_u32 v6, v21, v6, s8
	v_bfe_u32 v2, v7, 16, 1
	v_add3_u32 v2, v7, v2, s8
	v_bfe_u32 v3, v9, 16, 1
	v_lshrrev_b32_e32 v2, 16, v2
	v_add3_u32 v3, v9, v3, s8
	v_and_or_b32 v2, v3, s9, v2
	v_bfe_u32 v3, v11, 16, 1
	v_add3_u32 v3, v11, v3, s8
	v_bfe_u32 v4, v13, 16, 1
	v_lshrrev_b32_e32 v3, 16, v3
	v_add3_u32 v4, v13, v4, s8
	v_and_or_b32 v3, v4, s9, v3
	v_bfe_u32 v4, v15, 16, 1
	v_add3_u32 v4, v15, v4, s8
	v_bfe_u32 v5, v17, 16, 1
	v_lshrrev_b32_e32 v4, 16, v4
	v_add3_u32 v5, v17, v5, s8
	v_and_or_b32 v4, v5, s9, v4
	v_bfe_u32 v5, v19, 16, 1
	v_add3_u32 v5, v19, v5, s8
	v_lshrrev_b32_e32 v5, 16, v5
	v_and_or_b32 v5, v6, s9, v5
	v_or_b32_e32 v6, s0, v71
	v_lshlrev_b32_e32 v38, 11, v6
	v_lshl_add_u64 v[6:7], v[34:35], 0, v[38:39]
	global_store_dwordx4 v[6:7], v[2:5], off nt
	s_waitcnt lgkmcnt(0)
	s_and_saveexec_b64 s[0:1], s[2:3]
	s_cbranch_execz .LBB0_542

.LBB0_612:
	v_lshl_add_u64 v[194:195], s[82:83], 0, v[184:185]
	v_mul_f32_e32 v8, v50, v228
	s_nop 5
	v_fmac_f32_e32 v8, v66, v198
	v_mul_f32_e32 v11, v51, v229
	v_fmac_f32_e32 v11, v67, v199
	v_mul_f32_e32 v13, v52, v230
	v_fmac_f32_e32 v13, v68, v200
	s_nop 0
	v_cvt_pk_bf16_f32 v10, v8, v11
	ds_write_b16 v154, v10
	ds_write_b16_d16_hi v154, v10 offset:64
	v_mul_f32_e32 v15, v53, v231
	v_fmac_f32_e32 v15, v69, v201
	s_nop 0
	v_cvt_pk_bf16_f32 v14, v13, v15
	ds_write_b16 v154, v14 offset:128
	ds_write_b16_d16_hi v154, v14 offset:192
	v_mul_f32_e32 v17, v54, v232
	v_fmac_f32_e32 v17, v70, v206
	v_mul_f32_e32 v51, v55, v233
	v_fmac_f32_e32 v51, v71, v207
	v_cvt_pk_bf16_f32 v50, v17, v51
	ds_write_b16 v154, v50 offset:512
	ds_write_b16_d16_hi v154, v50 offset:576
	v_mul_f32_e32 v53, v56, v234
	v_fmac_f32_e32 v53, v72, v208
	v_mul_f32_e32 v55, v57, v235
	v_fmac_f32_e32 v55, v73, v209
	s_nop 0
	v_cvt_pk_bf16_f32 v54, v53, v55
	ds_write_b16 v154, v54 offset:640
	ds_write_b16_d16_hi v154, v54 offset:704
	v_mul_f32_e32 v57, v58, v236
	v_fmac_f32_e32 v57, v74, v210
	s_nop 0
	v_mul_f32_e32 v59, v59, v237
	v_fmac_f32_e32 v59, v75, v211
	v_cvt_pk_bf16_f32 v58, v57, v59
	ds_write_b16 v154, v58 offset:1024
	ds_write_b16_d16_hi v154, v58 offset:1088
	v_mul_f32_e32 v60, v60, v238
	v_fmac_f32_e32 v60, v76, v212
	s_nop 0
	v_mul_f32_e32 v61, v61, v239
	v_fmac_f32_e32 v61, v77, v213
	v_cvt_pk_bf16_f32 v67, v60, v61
	ds_write_b16 v154, v67 offset:1152
	ds_write_b16_d16_hi v154, v67 offset:1216
	v_mul_f32_e32 v62, v62, v240
	v_fmac_f32_e32 v62, v78, v214
	s_nop 0
	v_mul_f32_e32 v63, v63, v241
	v_fmac_f32_e32 v63, v79, v215
	v_cvt_pk_bf16_f32 v69, v62, v63
	ds_write_b16 v154, v69 offset:1536
	ds_write_b16_d16_hi v154, v69 offset:1600
	v_mul_f32_e32 v7, v64, v242
	v_mul_f32_e32 v65, v65, v243
	v_fmac_f32_e32 v7, v80, v216
	v_fmac_f32_e32 v65, v81, v217
	v_cvt_pk_bf16_f32 v3, v7, v65
	ds_write_b16 v154, v3 offset:1664
	ds_write_b16_d16_hi v154, v3 offset:1728
	s_mov_b64 s[70:71], 0x10000
	v_lshl_add_u64 v[196:197], v[194:195], 0, s[70:71]
	s_waitcnt lgkmcnt(0)
	ds_read_b128 v[160:163], v155
	ds_read_b128 v[164:167], v155 offset:1024
	s_mov_b32 vcc_lo, 0xaaaaaaaa
	s_mov_b32 vcc_hi, 0xaaaaaaaa
	v_cndmask_b32_e32 v3, v8, v11, vcc
	v_cndmask_b32_e32 v4, v13, v15, vcc
	v_cndmask_b32_e32 v5, v17, v51, vcc
	v_cndmask_b32_e32 v6, v53, v55, vcc
	v_cndmask_b32_e32 v9, v57, v59, vcc
	v_cndmask_b32_e32 v10, v60, v61, vcc
	v_cndmask_b32_e32 v12, v62, v63, vcc
	v_cndmask_b32_e32 v14, v7, v65, vcc
	v_cndmask_b32_e32 v11, v11, v8, vcc
	v_cndmask_b32_e32 v15, v15, v13, vcc
	v_cndmask_b32_e32 v51, v51, v17, vcc
	v_cndmask_b32_e32 v55, v55, v53, vcc
	v_cndmask_b32_e32 v59, v59, v57, vcc
	v_cndmask_b32_e32 v61, v61, v60, vcc
	v_cndmask_b32_e32 v63, v63, v62, vcc
	v_cndmask_b32_e32 v65, v65, v7, vcc
	v_mul_f32_e32 v8, v3, v3
	v_mul_f32_e32 v13, v4, v4
	v_mul_f32_e32 v17, v5, v5
	v_mul_f32_e32 v53, v6, v6
	v_mul_f32_e32 v57, v9, v9
	v_mul_f32_e32 v60, v10, v10
	v_mul_f32_e32 v62, v12, v12
	v_mul_f32_e32 v7, v14, v14
	v_mul_f32_e32 v11, v11, v11
	v_mul_f32_e32 v15, v15, v15
	v_mul_f32_e32 v51, v51, v51
	v_mul_f32_e32 v55, v55, v55
	v_mul_f32_e32 v59, v59, v59
	v_mul_f32_e32 v61, v61, v61
	v_mul_f32_e32 v63, v63, v63
	v_mul_f32_e32 v65, v65, v65
	v_add_f32_dpp v8, v11, v8 quad_perm:[1,0,3,2] row_mask:0xf bank_mask:0xf
	v_add_f32_dpp v13, v15, v13 quad_perm:[1,0,3,2] row_mask:0xf bank_mask:0xf
	v_add_f32_dpp v17, v51, v17 quad_perm:[1,0,3,2] row_mask:0xf bank_mask:0xf
	v_add_f32_dpp v53, v55, v53 quad_perm:[1,0,3,2] row_mask:0xf bank_mask:0xf
	v_add_f32_dpp v57, v59, v57 quad_perm:[1,0,3,2] row_mask:0xf bank_mask:0xf
	v_add_f32_dpp v60, v61, v60 quad_perm:[1,0,3,2] row_mask:0xf bank_mask:0xf
	v_add_f32_dpp v62, v63, v62 quad_perm:[1,0,3,2] row_mask:0xf bank_mask:0xf
	v_add_f32_dpp v7, v65, v7 quad_perm:[1,0,3,2] row_mask:0xf bank_mask:0xf
	s_mov_b32 vcc_lo, 0xcccccccc
	s_mov_b32 vcc_hi, 0xcccccccc
	v_add_f32_dpp v8, v8, v8 quad_perm:[2,3,0,1] row_mask:0xf bank_mask:0xf
	v_add_f32_dpp v13, v13, v13 quad_perm:[2,3,0,1] row_mask:0xf bank_mask:0xf
	v_add_f32_dpp v17, v17, v17 quad_perm:[2,3,0,1] row_mask:0xf bank_mask:0xf
	v_add_f32_dpp v53, v53, v53 quad_perm:[2,3,0,1] row_mask:0xf bank_mask:0xf
	v_add_f32_dpp v57, v57, v57 quad_perm:[2,3,0,1] row_mask:0xf bank_mask:0xf
	v_add_f32_dpp v60, v60, v60 quad_perm:[2,3,0,1] row_mask:0xf bank_mask:0xf
	v_add_f32_dpp v62, v62, v62 quad_perm:[2,3,0,1] row_mask:0xf bank_mask:0xf
	v_add_f32_dpp v7, v7, v7 quad_perm:[2,3,0,1] row_mask:0xf bank_mask:0xf
	v_cndmask_b32_e32 v8, v8, v13, vcc
	v_cndmask_b32_e32 v17, v17, v53, vcc
	v_cndmask_b32_e32 v57, v57, v60, vcc
	v_cndmask_b32_e32 v62, v62, v7, vcc
	s_nop 1
	v_add_f32_dpp v16, v8, v8 row_shl:4 row_mask:0xf bank_mask:0x5
	v_add_f32_dpp v16, v17, v17 row_shr:4 row_mask:0xf bank_mask:0xa
	v_add_f32_dpp v50, v57, v57 row_shl:4 row_mask:0xf bank_mask:0x5
	v_add_f32_dpp v50, v62, v62 row_shr:4 row_mask:0xf bank_mask:0xa
	s_nop 1
	v_add_f32_dpp v12, v16, v16 row_shl:8 row_mask:0xf bank_mask:0x3
	v_add_f32_dpp v12, v50, v50 row_shr:8 row_mask:0xf bank_mask:0xc
	s_waitcnt lgkmcnt(0)
	global_store_dwordx4 v[194:195], v[160:163], off nt
	global_store_dwordx4 v[196:197], v[164:167], off nt
	v_mov_b32_e32 v14, v12
	v_lshl_add_u64 v[4:5], s[82:83], 0, v[182:183]
	s_nop 0
	v_permlane16_swap_b32_e32 v12, v14
	s_mov_b64 s[70:71], exec
	v_add_f32_e32 v12, v12, v14
	s_mov_b32 exec_lo, 0xffff
	s_mov_b32 exec_hi, 0xffff
	global_store_dword v[4:5], v12, off
	s_branch .LBB0_592
